# LRU pass2: hoist 32 gate loads per block ahead of serialized load-wait-store chain; pipeline 8-deep chunk-carry loads with counted vmcnt
# speedup vs baseline: 1.0106x; 1.0106x over previous
; DI float bf2f(u16 h) { return __uint_as_float(((uint32_t)h) << 16); }
; DI float sigmoidf_(float x) { return __builtin_amdgcn_rcpf(1.f + __expf(-x)); }
; template <bool FINAL>
; DI void lru_item(int ws, PP p, char* shm, int item) {
;     ...
;     const int j = nb * 32 + rl, chj = wid * 64 + j;
;     const float baj = p->ba[chj], bxj = p->bx[chj];
;     const float la = -8.f * log1pf(__expf(-p->lam[chj]));
; #pragma unroll
;     for (int mb = 0; mb < 2; ++mb)
; #pragma unroll
;       for (int i = 0; i < 16; ++i) {
;         const int tok = mb * 32 + hh * 4 + (i & 3) + 8 * (i >> 2);
;         const float xc = bf2f(XC[tok * KVS + j]);
;         const float r = sigmoidf_(ar[mb][i] + baj), ig = sigmoidf_(ai[mb][i] + bxj);
;         const float aa = __expf(r * la);
;         ar[mb][i] = aa;
;         ai[mb][i] = __builtin_amdgcn_sqrtf(__builtin_fmaf(-aa, aa, 1.f)) * ig * xc;
;       }
.LBB0_674:
	s_waitcnt vmcnt(0)
	v_mul_f32_e32 v72, 0xbfb8aa3b, v102
	v_exp_f32_e32 v72, v72
	v_add_f32_e32 v48, v48, v111
	v_mul_f32_e32 v48, 0xbfb8aa3b, v48
	v_exp_f32_e32 v48, v48
	v_add_f32_e32 v76, 1.0, v72
	v_add_f32_e32 v74, -1.0, v76
	v_sub_f32_e32 v75, v74, v76
	v_add_f32_e32 v75, 1.0, v75
	v_sub_f32_e32 v74, v72, v74
	v_add_f32_e32 v77, v74, v75
	v_frexp_mant_f32_e32 v74, v76
	v_cmp_gt_f32_e32 vcc, s85, v74
	v_cvt_f64_f32_e32 v[74:75], v76
	v_frexp_exp_i32_f64_e32 v74, v[74:75]
	v_subbrev_co_u32_e32 v74, vcc, 0, v74, vcc
	v_sub_u32_e32 v75, 0, v74
	v_ldexp_f32 v76, v76, v75
	v_ldexp_f32 v75, v77, v75
	v_add_f32_e32 v77, -1.0, v76
	v_add_f32_e32 v102, 1.0, v77
	v_sub_f32_e32 v102, v76, v102
	v_add_f32_e32 v102, v75, v102
	v_add_f32_e32 v103, v77, v102
	v_sub_f32_e32 v77, v103, v77
	v_sub_f32_e32 v77, v102, v77
	v_add_f32_e32 v102, 1.0, v76
	v_add_f32_e32 v104, -1.0, v102
	v_sub_f32_e32 v76, v76, v104
	v_add_f32_e32 v75, v75, v76
	v_add_f32_e32 v76, v102, v75
	v_sub_f32_e32 v102, v76, v102
	v_sub_f32_e32 v75, v75, v102
	v_rcp_f32_e32 v102, v76
	v_cvt_f32_i32_e32 v74, v74
	v_cmp_neq_f32_e32 vcc, s87, v72
	v_add_f32_e32 v48, 1.0, v48
	v_mul_f32_e32 v104, v103, v102
	v_mul_f32_e32 v105, v76, v104
	v_fma_f32 v106, v104, v76, -v105
	v_fmac_f32_e32 v106, v104, v75
	v_add_f32_e32 v107, v105, v106
	v_sub_f32_e32 v108, v103, v107
	v_sub_f32_e32 v103, v103, v108
	v_sub_f32_e32 v105, v107, v105
	v_sub_f32_e32 v103, v103, v107
	v_add_f32_e32 v77, v77, v103
	v_sub_f32_e32 v103, v105, v106
	v_add_f32_e32 v77, v103, v77
	v_add_f32_e32 v103, v108, v77
	v_mul_f32_e32 v105, v102, v103
	v_mul_f32_e32 v106, v76, v105
	v_fma_f32 v76, v105, v76, -v106
	v_fmac_f32_e32 v76, v105, v75
	v_sub_f32_e32 v75, v108, v103
	v_add_f32_e32 v75, v77, v75
	v_add_f32_e32 v77, v106, v76
	v_sub_f32_e32 v107, v103, v77
	v_sub_f32_e32 v103, v103, v107
	v_sub_f32_e32 v106, v77, v106
	v_sub_f32_e32 v77, v103, v77
	v_add_f32_e32 v75, v75, v77
	v_sub_f32_e32 v76, v106, v76
	v_add_f32_e32 v75, v76, v75
	v_add_f32_e32 v76, v104, v105
	v_add_f32_e32 v75, v107, v75
	v_sub_f32_e32 v77, v76, v104
	v_mul_f32_e32 v75, v102, v75
	v_sub_f32_e32 v77, v105, v77
	v_add_f32_e32 v75, v77, v75
	v_mul_f32_e32 v104, 0x3f317218, v74
	v_add_f32_e32 v77, v76, v75
	v_fma_f32 v105, v74, s86, -v104
	v_mul_f32_e32 v102, v77, v77
	v_fmac_f32_e32 v105, 0xb102e308, v74
	v_sub_f32_e32 v74, v77, v76
	v_fmamk_f32 v103, v102, 0x3e9b6dac, v79
	v_sub_f32_e32 v74, v75, v74
	v_add_f32_e32 v75, v104, v105
	v_fmaak_f32 v103, v102, v103, 0x3f2aaada
	v_sub_f32_e32 v76, v75, v104
	v_ldexp_f32 v104, v77, 1
	v_mul_f32_e32 v77, v77, v102
	v_mul_f32_e32 v77, v77, v103
	v_add_f32_e32 v102, v104, v77
	v_sub_f32_e32 v103, v102, v104
	v_ldexp_f32 v74, v74, 1
	v_sub_f32_e32 v77, v77, v103
	v_add_f32_e32 v74, v74, v77
	v_add_f32_e32 v77, v102, v74
	v_sub_f32_e32 v102, v77, v102
	v_sub_f32_e32 v74, v74, v102
	v_add_f32_e32 v102, v75, v77
	v_sub_f32_e32 v103, v102, v75
	v_sub_f32_e32 v104, v102, v103
	v_sub_f32_e32 v76, v105, v76
	v_sub_f32_e32 v75, v75, v104
	v_sub_f32_e32 v77, v77, v103
	v_add_f32_e32 v75, v77, v75
	v_add_f32_e32 v77, v76, v74
	v_sub_f32_e32 v103, v77, v76
	v_sub_f32_e32 v104, v77, v103
	v_sub_f32_e32 v76, v76, v104
	v_sub_f32_e32 v74, v74, v103
	v_add_f32_e32 v75, v77, v75
	v_add_f32_e32 v74, v74, v76
	v_add_f32_e32 v76, v102, v75
	v_sub_f32_e32 v77, v76, v102
	v_sub_f32_e32 v75, v75, v77
	v_add_f32_e32 v74, v74, v75
	v_add_f32_e32 v74, v76, v74
	v_cndmask_b32_e32 v74, v80, v74, vcc
	v_cmp_ngt_f32_e32 vcc, -1.0, v72
	v_rcp_f32_e32 v48, v48
	v_add_f32_e32 v32, v32, v112
	v_cndmask_b32_e32 v74, v81, v74, vcc
	v_cmp_neq_f32_e32 vcc, -1.0, v72
	v_mul_f32_e32 v32, 0xbfb8aa3b, v32
	v_exp_f32_e32 v32, v32
	v_cndmask_b32_e32 v74, v82, v74, vcc
	v_cmp_lt_f32_e64 vcc, |v72|, s88
	v_add_f32_e32 v33, v33, v112
	v_add_f32_e32 v32, 1.0, v32
	v_cndmask_b32_e32 v72, v74, v72, vcc
	v_mul_f32_e32 v132, 0xc1000000, v72
	v_mul_f32_e32 v48, v48, v132
	v_mul_f32_e32 v48, 0x3fb8aa3b, v48
	v_exp_f32_e32 v110, v48
	v_rcp_f32_e32 v32, v32
	s_waitcnt lgkmcnt(14)
	v_lshlrev_b32_e32 v72, 16, v101
	v_mul_f32_e32 v33, 0xbfb8aa3b, v33
	v_fma_f32 v48, -v110, v110, 1.0
	v_sqrt_f32_e32 v48, v48
	v_exp_f32_e32 v33, v33
	v_lshlrev_b32_e32 v135, 16, v99
	v_lshlrev_b32_e32 v139, 16, v98
	v_mul_f32_e32 v32, v32, v48
	v_mul_f32_e32 v109, v32, v72
	v_add_f32_e32 v32, v49, v111
	v_mul_f32_e32 v32, 0xbfb8aa3b, v32
	v_exp_f32_e32 v32, v32
	v_add_f32_e32 v33, 1.0, v33
	v_rcp_f32_e32 v33, v33
	v_lshlrev_b32_e32 v77, 16, v90
	v_add_f32_e32 v32, 1.0, v32
	v_rcp_f32_e32 v32, v32
	v_lshlrev_b32_e32 v105, 16, v93
	v_lshlrev_b32_e32 v102, 16, v95
	v_lshlrev_b32_e32 v133, 16, v100
	v_mul_f32_e32 v32, v32, v132
	v_mul_f32_e32 v32, 0x3fb8aa3b, v32
	v_exp_f32_e32 v134, v32
	v_lshlrev_b32_e32 v100, 16, v96
	v_add_f32_e32 v16, v16, v111
	v_mul_f32_e32 v16, 0xbfb8aa3b, v16
	v_fma_f32 v32, -v134, v134, 1.0
	v_sqrt_f32_e32 v32, v32
	v_exp_f32_e32 v16, v16
	v_add_f32_e32 v0, v0, v112
	v_mul_f32_e32 v0, 0xbfb8aa3b, v0
	v_mul_f32_e32 v136, v33, v32
	v_add_f32_e32 v32, v50, v111
	v_mul_f32_e32 v32, 0xbfb8aa3b, v32
	v_exp_f32_e32 v32, v32
	v_add_f32_e32 v33, v34, v112
	v_mul_f32_e32 v33, 0xbfb8aa3b, v33
	v_exp_f32_e32 v33, v33
	v_add_f32_e32 v32, 1.0, v32
	v_rcp_f32_e32 v32, v32
	v_add_f32_e32 v34, v36, v112
	v_add_f32_e32 v33, 1.0, v33
	v_rcp_f32_e32 v33, v33
	v_mul_f32_e32 v32, v32, v132
	v_mul_f32_e32 v32, 0x3fb8aa3b, v32
	v_exp_f32_e32 v137, v32
	v_mul_f32_e32 v34, 0xbfb8aa3b, v34
	v_exp_f32_e32 v34, v34
	v_add_f32_e32 v16, 1.0, v16
	v_fma_f32 v32, -v137, v137, 1.0
	v_sqrt_f32_e32 v32, v32
	v_add_f32_e32 v34, 1.0, v34
	v_rcp_f32_e32 v34, v34
	v_rcp_f32_e32 v16, v16
	v_mul_f32_e32 v138, v33, v32
	v_add_f32_e32 v32, v51, v111
	v_mul_f32_e32 v32, 0xbfb8aa3b, v32
	v_exp_f32_e32 v32, v32
	v_add_f32_e32 v33, v35, v112
	v_mul_f32_e32 v33, 0xbfb8aa3b, v33
	v_exp_f32_e32 v33, v33
	v_add_f32_e32 v32, 1.0, v32
	v_rcp_f32_e32 v32, v32
	v_mul_f32_e32 v16, v16, v132
	v_add_f32_e32 v33, 1.0, v33
	v_rcp_f32_e32 v33, v33
	v_mul_f32_e32 v32, v32, v132
	v_mul_f32_e32 v32, 0x3fb8aa3b, v32
	v_exp_f32_e32 v140, v32
	v_mul_f32_e32 v16, 0x3fb8aa3b, v16
	v_exp_f32_e32 v0, v0
	v_add_f32_e32 v1, v1, v112
	v_fma_f32 v32, -v140, v140, 1.0
	v_sqrt_f32_e32 v32, v32
	v_add_f32_e32 v0, 1.0, v0
	v_rcp_f32_e32 v0, v0
	v_mul_f32_e32 v1, 0xbfb8aa3b, v1
	v_mul_f32_e32 v141, v33, v32
	v_add_f32_e32 v33, v52, v111
	v_mul_f32_e32 v33, 0xbfb8aa3b, v33
	v_exp_f32_e32 v33, v33
	v_lshlrev_b32_e32 v32, 16, v97
	v_exp_f32_e32 v1, v1
	v_fmac_f32_e32 v109, 0, v110
	v_add_f32_e32 v33, 1.0, v33
	v_rcp_f32_e32 v33, v33
	v_add_f32_e32 v1, 1.0, v1
	v_rcp_f32_e32 v1, v1
	v_lshlrev_b32_e32 v91, 16, v91
	v_mul_f32_e32 v33, v33, v132
	v_mul_f32_e32 v33, 0x3fb8aa3b, v33
	v_exp_f32_e32 v99, v33
	v_lshlrev_b32_e32 v94, 16, v94
	v_lshlrev_b32_e32 v64, 16, v64
	s_waitcnt lgkmcnt(13)
; DI float bf2f(u16 h) { return __uint_as_float(((uint32_t)h) << 16); }
; DI float sigmoidf_(float x) { return __builtin_amdgcn_rcpf(1.f + __expf(-x)); }
; template <bool FINAL>
; DI void lru_item(int ws, PP p, char* shm, int item) {
;     ...
; #pragma unroll
;     for (int mb = 0; mb < 2; ++mb)
; #pragma unroll
;       for (int i = 0; i < 16; ++i) {
;         const int tok = mb * 32 + hh * 4 + (i & 3) + 8 * (i >> 2);
;         const float xc = bf2f(XC[tok * KVS + j]);
;         const float r = sigmoidf_(ar[mb][i] + baj), ig = sigmoidf_(ai[mb][i] + bxj);
;         const float aa = __expf(r * la);
;         ar[mb][i] = aa;
;         ai[mb][i] = __builtin_amdgcn_sqrtf(__builtin_fmaf(-aa, aa, 1.f)) * ig * xc;
;       }
	v_lshlrev_b32_e32 v49, 16, v126
	v_fma_f32 v33, -v99, v99, 1.0
	v_sqrt_f32_e32 v33, v33
	s_waitcnt lgkmcnt(12)
	v_lshlrev_b32_e32 v52, 16, v125
	s_waitcnt lgkmcnt(10)
	v_lshlrev_b32_e32 v36, 16, v123
	s_xor_b64 s[46:47], s[48:49], -1
	v_mul_f32_e32 v33, v34, v33
	v_mul_f32_e32 v98, v33, v32
	v_add_f32_e32 v32, v53, v111
	v_mul_f32_e32 v32, 0xbfb8aa3b, v32
	v_exp_f32_e32 v32, v32
	v_add_f32_e32 v33, v37, v112
	v_mul_f32_e32 v33, 0xbfb8aa3b, v33
	v_exp_f32_e32 v33, v33
	v_add_f32_e32 v32, 1.0, v32
	v_rcp_f32_e32 v32, v32
	v_add_f32_e32 v34, v40, v112
	v_add_f32_e32 v33, 1.0, v33
	v_rcp_f32_e32 v33, v33
	v_mul_f32_e32 v32, v32, v132
	v_mul_f32_e32 v32, 0x3fb8aa3b, v32
	v_exp_f32_e32 v101, v32
	v_mul_f32_e32 v34, 0xbfb8aa3b, v34
	v_exp_f32_e32 v34, v34
	v_fmac_f32_e32 v98, 0, v99
	v_fma_f32 v32, -v101, v101, 1.0
	v_sqrt_f32_e32 v32, v32
	v_add_f32_e32 v34, 1.0, v34
	v_rcp_f32_e32 v34, v34
	s_mov_b32 s22, 1
	v_mul_f32_e32 v103, v33, v32
	v_add_f32_e32 v32, v54, v111
	v_mul_f32_e32 v32, 0xbfb8aa3b, v32
	v_exp_f32_e32 v32, v32
	v_add_f32_e32 v33, v38, v112
	v_mul_f32_e32 v33, 0xbfb8aa3b, v33
	v_exp_f32_e32 v33, v33
	v_add_f32_e32 v32, 1.0, v32
	v_rcp_f32_e32 v32, v32
	s_waitcnt lgkmcnt(9)
	v_lshlrev_b32_e32 v38, 16, v122
	v_add_f32_e32 v33, 1.0, v33
	v_rcp_f32_e32 v33, v33
	v_mul_f32_e32 v32, v32, v132
	v_mul_f32_e32 v32, 0x3fb8aa3b, v32
	v_exp_f32_e32 v104, v32
	s_mov_b64 s[48:49], 0
	s_and_b64 vcc, exec, s[46:47]
	v_fma_f32 v32, -v104, v104, 1.0
	v_sqrt_f32_e32 v32, v32
	s_nop 0
	v_mul_f32_e32 v106, v33, v32
	v_add_f32_e32 v32, v55, v111
	v_mul_f32_e32 v32, 0xbfb8aa3b, v32
	v_exp_f32_e32 v32, v32
	v_add_f32_e32 v33, v39, v112
	v_mul_f32_e32 v33, 0xbfb8aa3b, v33
	v_exp_f32_e32 v33, v33
	v_add_f32_e32 v32, 1.0, v32
	v_rcp_f32_e32 v32, v32
	v_add_f32_e32 v33, 1.0, v33
	v_rcp_f32_e32 v33, v33
	v_mul_f32_e32 v32, v32, v132
	v_mul_f32_e32 v32, 0x3fb8aa3b, v32
	v_exp_f32_e32 v107, v32
	s_nop 0
	v_fma_f32 v32, -v107, v107, 1.0
	v_sqrt_f32_e32 v32, v32
	s_nop 0
	v_mul_f32_e32 v108, v33, v32
	v_add_f32_e32 v33, v56, v111
	v_mul_f32_e32 v33, 0xbfb8aa3b, v33
	v_exp_f32_e32 v33, v33
	v_lshlrev_b32_e32 v32, 16, v92
	v_add_f32_e32 v33, 1.0, v33
	v_rcp_f32_e32 v33, v33
	s_nop 0
	v_mul_f32_e32 v33, v33, v132
	v_mul_f32_e32 v33, 0x3fb8aa3b, v33
	v_exp_f32_e32 v76, v33
	s_nop 0
	v_fma_f32 v33, -v76, v76, 1.0
	v_sqrt_f32_e32 v33, v33
	s_nop 0
	v_mul_f32_e32 v33, v34, v33
	v_mul_f32_e32 v75, v33, v32
	v_add_f32_e32 v32, v57, v111
	v_mul_f32_e32 v32, 0xbfb8aa3b, v32
	v_exp_f32_e32 v32, v32
	v_add_f32_e32 v33, v41, v112
	v_mul_f32_e32 v33, 0xbfb8aa3b, v33
	v_exp_f32_e32 v33, v33
	v_add_f32_e32 v32, 1.0, v32
	v_rcp_f32_e32 v32, v32
	v_add_f32_e32 v34, v44, v112
	v_add_f32_e32 v33, 1.0, v33
	v_rcp_f32_e32 v33, v33
	v_mul_f32_e32 v32, v32, v132
	v_mul_f32_e32 v32, 0x3fb8aa3b, v32
	v_exp_f32_e32 v90, v32
	v_mul_f32_e32 v34, 0xbfb8aa3b, v34
	v_exp_f32_e32 v34, v34
	v_fmac_f32_e32 v75, 0, v76
	v_fma_f32 v32, -v90, v90, 1.0
	v_sqrt_f32_e32 v32, v32
	v_add_f32_e32 v34, 1.0, v34
	v_rcp_f32_e32 v34, v34
	s_waitcnt lgkmcnt(8)
	v_lshlrev_b32_e32 v41, 16, v121
	v_mul_f32_e32 v92, v33, v32
	v_add_f32_e32 v32, v58, v111
	v_mul_f32_e32 v32, 0xbfb8aa3b, v32
	v_exp_f32_e32 v32, v32
	v_add_f32_e32 v33, v42, v112
	v_mul_f32_e32 v33, 0xbfb8aa3b, v33
	v_exp_f32_e32 v33, v33
	v_add_f32_e32 v32, 1.0, v32
	v_rcp_f32_e32 v32, v32
	v_lshlrev_b32_e32 v58, 16, v130
	v_add_f32_e32 v33, 1.0, v33
	v_rcp_f32_e32 v33, v33
	v_mul_f32_e32 v32, v32, v132
	v_mul_f32_e32 v32, 0x3fb8aa3b, v32
	v_exp_f32_e32 v93, v32
	s_nop 0
	v_fma_f32 v32, -v93, v93, 1.0
	v_sqrt_f32_e32 v32, v32
	s_nop 0
	v_mul_f32_e32 v95, v33, v32
	v_add_f32_e32 v32, v59, v111
	v_mul_f32_e32 v32, 0xbfb8aa3b, v32
	v_exp_f32_e32 v32, v32
	v_add_f32_e32 v33, v43, v112
	v_mul_f32_e32 v33, 0xbfb8aa3b, v33
	v_exp_f32_e32 v33, v33
	v_add_f32_e32 v32, 1.0, v32
	v_rcp_f32_e32 v32, v32
	v_add_f32_e32 v33, 1.0, v33
	v_rcp_f32_e32 v33, v33
	v_mul_f32_e32 v32, v32, v132
	v_mul_f32_e32 v32, 0x3fb8aa3b, v32
	v_exp_f32_e32 v96, v32
	s_nop 0
	v_fma_f32 v32, -v96, v96, 1.0
	v_sqrt_f32_e32 v32, v32
	s_nop 0
	v_mul_f32_e32 v97, v33, v32
	v_add_f32_e32 v33, v60, v111
	v_mul_f32_e32 v33, 0xbfb8aa3b, v33
	v_exp_f32_e32 v33, v33
	v_lshlrev_b32_e32 v32, 16, v131
	v_lshlrev_b32_e32 v60, 16, v129
	v_add_f32_e32 v33, 1.0, v33
	v_rcp_f32_e32 v33, v33
	s_nop 0
	v_mul_f32_e32 v33, v33, v132
	v_mul_f32_e32 v33, 0x3fb8aa3b, v33
	v_exp_f32_e32 v57, v33
	s_nop 0
	v_fma_f32 v33, -v57, v57, 1.0
	v_sqrt_f32_e32 v33, v33
	s_nop 0
	v_mul_f32_e32 v33, v34, v33
	v_mul_f32_e32 v56, v33, v32
	v_add_f32_e32 v32, v61, v111
	v_mul_f32_e32 v32, 0xbfb8aa3b, v32
	v_exp_f32_e32 v32, v32
	v_add_f32_e32 v33, v45, v112
	v_mul_f32_e32 v33, 0xbfb8aa3b, v33
	v_exp_f32_e32 v33, v33
	v_add_f32_e32 v32, 1.0, v32
	v_rcp_f32_e32 v32, v32
	v_fmac_f32_e32 v56, 0, v57
	v_add_f32_e32 v33, 1.0, v33
	v_rcp_f32_e32 v33, v33
	v_mul_f32_e32 v32, v32, v132
	v_mul_f32_e32 v32, 0x3fb8aa3b, v32
	v_exp_f32_e32 v59, v32
	s_nop 0
	v_fma_f32 v32, -v59, v59, 1.0
	v_sqrt_f32_e32 v32, v32
	s_nop 0
	v_mul_f32_e32 v61, v33, v32
	v_add_f32_e32 v32, v62, v111
	v_mul_f32_e32 v32, 0xbfb8aa3b, v32
	v_exp_f32_e32 v32, v32
	v_add_f32_e32 v33, v46, v112
	v_mul_f32_e32 v33, 0xbfb8aa3b, v33
	v_exp_f32_e32 v33, v33
	v_add_f32_e32 v32, 1.0, v32
	v_rcp_f32_e32 v32, v32
	v_exp_f32_e32 v46, v16
	v_add_f32_e32 v33, 1.0, v33
	v_rcp_f32_e32 v33, v33
	v_mul_f32_e32 v32, v32, v132
	v_mul_f32_e32 v32, 0x3fb8aa3b, v32
	v_exp_f32_e32 v62, v32
	v_fma_f32 v16, -v46, v46, 1.0
	v_sqrt_f32_e32 v16, v16
	v_fma_f32 v32, -v62, v62, 1.0
	v_sqrt_f32_e32 v32, v32
	v_mul_f32_e32 v0, v0, v16
	s_waitcnt lgkmcnt(0)
; DI float bf2f(u16 h) { return __uint_as_float(((uint32_t)h) << 16); }
; DI float sigmoidf_(float x) { return __builtin_amdgcn_rcpf(1.f + __expf(-x)); }
; template <bool FINAL>
; DI void lru_item(int ws, PP p, char* shm, int item) {
;     ...
; #pragma unroll
;     for (int mb = 0; mb < 2; ++mb)
; #pragma unroll
;       for (int i = 0; i < 16; ++i) {
;         const int tok = mb * 32 + hh * 4 + (i & 3) + 8 * (i >> 2);
;         const float xc = bf2f(XC[tok * KVS + j]);
;         const float r = sigmoidf_(ar[mb][i] + baj), ig = sigmoidf_(ai[mb][i] + bxj);
;         const float aa = __expf(r * la);
;         ar[mb][i] = aa;
;         ai[mb][i] = __builtin_amdgcn_sqrtf(__builtin_fmaf(-aa, aa, 1.f)) * ig * xc;
;       }
;     ...
; #pragma unroll
;     for (int mb = 0; mb < 2; ++mb)
; #pragma unroll
;       for (int q = 0; q < 4; ++q) {
;         float P = 1.f, H = 0.f;
; #pragma unroll
;         for (int e = 0; e < 4; ++e) {
;           const int idx = 4 * q + e;
;           H = ar[mb][idx] * H + ai[mb][idx];
;           P *= ar[mb][idx];
;           ar[mb][idx] = P;
;           ai[mb][idx] = H;
;         }
	v_lshlrev_b32_e32 v16, 16, v113
	v_mul_f32_e32 v113, v134, v109
	v_mul_f32_e32 v72, v33, v32
	v_add_f32_e32 v32, v63, v111
	v_mul_f32_e32 v32, 0xbfb8aa3b, v32
	v_exp_f32_e32 v32, v32
	v_add_f32_e32 v33, v47, v112
	v_mul_f32_e32 v33, 0xbfb8aa3b, v33
	v_exp_f32_e32 v33, v33
	v_add_f32_e32 v32, 1.0, v32
	v_rcp_f32_e32 v32, v32
	v_fmac_f32_e32 v113, v136, v133
	v_add_f32_e32 v33, 1.0, v33
	v_rcp_f32_e32 v33, v33
	v_mul_f32_e32 v32, v32, v132
	v_mul_f32_e32 v32, 0x3fb8aa3b, v32
	v_exp_f32_e32 v63, v32
	v_lshlrev_b32_e32 v47, 16, v127
	v_fma_f32 v32, -v63, v63, 1.0
	v_sqrt_f32_e32 v32, v32
	s_nop 0
	v_mul_f32_e32 v74, v33, v32
	v_lshlrev_b32_e32 v32, 16, v128
	v_mul_f32_e32 v45, v0, v32
	v_add_f32_e32 v0, v17, v111
	v_mul_f32_e32 v0, 0xbfb8aa3b, v0
	v_exp_f32_e32 v0, v0
	v_fmac_f32_e32 v45, 0, v46
	v_add_f32_e32 v0, 1.0, v0
	v_rcp_f32_e32 v0, v0
	s_nop 0
	v_mul_f32_e32 v0, v0, v132
	v_mul_f32_e32 v0, 0x3fb8aa3b, v0
	v_exp_f32_e32 v48, v0
	s_nop 0
	v_fma_f32 v0, -v48, v48, 1.0
	v_sqrt_f32_e32 v0, v0
	s_nop 0
	v_mul_f32_e32 v50, v1, v0
	v_add_f32_e32 v0, v18, v111
	v_mul_f32_e32 v0, 0xbfb8aa3b, v0
	v_exp_f32_e32 v0, v0
	v_add_f32_e32 v1, v2, v112
	v_mul_f32_e32 v1, 0xbfb8aa3b, v1
	v_exp_f32_e32 v1, v1
	v_add_f32_e32 v0, 1.0, v0
	v_rcp_f32_e32 v0, v0
	v_add_f32_e32 v2, v4, v112
	v_add_f32_e32 v1, 1.0, v1
	v_rcp_f32_e32 v1, v1
	v_mul_f32_e32 v0, v0, v132
	v_mul_f32_e32 v0, 0x3fb8aa3b, v0
	v_exp_f32_e32 v51, v0
	v_mul_f32_e32 v2, 0xbfb8aa3b, v2
	v_exp_f32_e32 v2, v2
	v_fma_f32 v0, -v51, v51, 1.0
	v_sqrt_f32_e32 v0, v0
	v_add_f32_e32 v2, 1.0, v2
	v_rcp_f32_e32 v2, v2
	v_mul_f32_e32 v53, v1, v0
	v_add_f32_e32 v0, v19, v111
	v_mul_f32_e32 v0, 0xbfb8aa3b, v0
	v_exp_f32_e32 v0, v0
	v_add_f32_e32 v1, v3, v112
	v_mul_f32_e32 v1, 0xbfb8aa3b, v1
	v_exp_f32_e32 v1, v1
	v_add_f32_e32 v0, 1.0, v0
	v_rcp_f32_e32 v0, v0
	v_add_f32_e32 v1, 1.0, v1
	v_rcp_f32_e32 v1, v1
	v_mul_f32_e32 v0, v0, v132
	v_mul_f32_e32 v0, 0x3fb8aa3b, v0
	v_exp_f32_e32 v54, v0
	s_nop 0
	v_fma_f32 v0, -v54, v54, 1.0
	v_sqrt_f32_e32 v0, v0
	s_nop 0
	v_mul_f32_e32 v55, v1, v0
	v_add_f32_e32 v1, v20, v111
	v_mul_f32_e32 v1, 0xbfb8aa3b, v1
	v_exp_f32_e32 v1, v1
	v_lshlrev_b32_e32 v0, 16, v124
	v_add_f32_e32 v1, 1.0, v1
	v_rcp_f32_e32 v1, v1
	s_nop 0
	v_mul_f32_e32 v1, v1, v132
	v_mul_f32_e32 v1, 0x3fb8aa3b, v1
	v_exp_f32_e32 v35, v1
	s_nop 0
	v_fma_f32 v1, -v35, v35, 1.0
	v_sqrt_f32_e32 v1, v1
	s_nop 0
	v_mul_f32_e32 v1, v2, v1
	v_mul_f32_e32 v34, v1, v0
	v_add_f32_e32 v0, v21, v111
	v_mul_f32_e32 v0, 0xbfb8aa3b, v0
	v_exp_f32_e32 v0, v0
	v_add_f32_e32 v1, v5, v112
	v_mul_f32_e32 v1, 0xbfb8aa3b, v1
	v_exp_f32_e32 v1, v1
	v_add_f32_e32 v0, 1.0, v0
	v_rcp_f32_e32 v0, v0
	v_add_f32_e32 v2, v8, v112
	v_add_f32_e32 v1, 1.0, v1
	v_rcp_f32_e32 v1, v1
	v_mul_f32_e32 v0, v0, v132
	v_mul_f32_e32 v0, 0x3fb8aa3b, v0
	v_exp_f32_e32 v37, v0
	v_mul_f32_e32 v2, 0xbfb8aa3b, v2
	v_exp_f32_e32 v2, v2
	v_mov_b64_e32 v[4:5], s[30:31]
	v_fma_f32 v0, -v37, v37, 1.0
	v_sqrt_f32_e32 v0, v0
	v_add_f32_e32 v2, 1.0, v2
	v_rcp_f32_e32 v2, v2
	v_fmac_f32_e32 v34, 0, v35
	v_mul_f32_e32 v39, v1, v0
	v_add_f32_e32 v0, v22, v111
	v_mul_f32_e32 v0, 0xbfb8aa3b, v0
	v_exp_f32_e32 v0, v0
	v_add_f32_e32 v1, v6, v112
	v_mul_f32_e32 v1, 0xbfb8aa3b, v1
	v_exp_f32_e32 v1, v1
	v_add_f32_e32 v0, 1.0, v0
	v_rcp_f32_e32 v0, v0
	v_mov_b32_e32 v6, v86
	v_add_f32_e32 v1, 1.0, v1
	v_rcp_f32_e32 v1, v1
	v_mul_f32_e32 v0, v0, v132
	v_mul_f32_e32 v0, 0x3fb8aa3b, v0
	v_exp_f32_e32 v40, v0
	s_load_dwordx2 s[0:1], s[16:17], 0x128
	v_lshlrev_b32_e32 v21, 16, v119
	v_fma_f32 v0, -v40, v40, 1.0
	v_sqrt_f32_e32 v0, v0
	s_nop 0
	v_mul_f32_e32 v42, v1, v0
	v_add_f32_e32 v0, v23, v111
	v_mul_f32_e32 v0, 0xbfb8aa3b, v0
	v_exp_f32_e32 v0, v0
	v_add_f32_e32 v1, v7, v112
	v_mul_f32_e32 v1, 0xbfb8aa3b, v1
	v_exp_f32_e32 v1, v1
	v_add_f32_e32 v0, 1.0, v0
	v_rcp_f32_e32 v0, v0
	v_ashrrev_i32_e32 v7, 31, v6
	v_add_f32_e32 v1, 1.0, v1
	v_rcp_f32_e32 v1, v1
	v_mul_f32_e32 v0, v0, v132
	v_mul_f32_e32 v0, 0x3fb8aa3b, v0
	v_exp_f32_e32 v43, v0
	v_lshlrev_b32_e32 v23, 16, v118
	v_fma_f32 v0, -v43, v43, 1.0
	v_sqrt_f32_e32 v0, v0
	s_nop 0
	v_mul_f32_e32 v44, v1, v0
	v_add_f32_e32 v1, v24, v111
	v_mul_f32_e32 v1, 0xbfb8aa3b, v1
	v_exp_f32_e32 v1, v1
	v_lshlrev_b32_e32 v0, 16, v120
	v_add_f32_e32 v1, 1.0, v1
	v_rcp_f32_e32 v1, v1
	s_nop 0
	v_mul_f32_e32 v1, v1, v132
	v_mul_f32_e32 v1, 0x3fb8aa3b, v1
	v_exp_f32_e32 v20, v1
	s_nop 0
	v_fma_f32 v1, -v20, v20, 1.0
	v_sqrt_f32_e32 v1, v1
	s_nop 0
	v_mul_f32_e32 v1, v2, v1
	v_mul_f32_e32 v19, v1, v0
	v_add_f32_e32 v0, v25, v111
	v_mul_f32_e32 v0, 0xbfb8aa3b, v0
	v_exp_f32_e32 v0, v0
	v_add_f32_e32 v1, v9, v112
	v_mul_f32_e32 v1, 0xbfb8aa3b, v1
	v_exp_f32_e32 v1, v1
	v_add_f32_e32 v0, 1.0, v0
	v_rcp_f32_e32 v0, v0
	v_add_f32_e32 v2, v12, v112
	v_add_f32_e32 v1, 1.0, v1
	v_rcp_f32_e32 v1, v1
	v_mul_f32_e32 v0, v0, v132
	v_mul_f32_e32 v0, 0x3fb8aa3b, v0
	v_exp_f32_e32 v22, v0
	v_mul_f32_e32 v2, 0xbfb8aa3b, v2
	v_exp_f32_e32 v2, v2
	v_lshlrev_b32_e32 v12, 16, v114
	v_fma_f32 v0, -v22, v22, 1.0
	v_sqrt_f32_e32 v0, v0
	v_add_f32_e32 v2, 1.0, v2
	v_rcp_f32_e32 v2, v2
	v_fmac_f32_e32 v19, 0, v20
	v_mul_f32_e32 v24, v1, v0
	v_add_f32_e32 v0, v26, v111
	v_mul_f32_e32 v0, 0xbfb8aa3b, v0
	v_exp_f32_e32 v0, v0
	v_add_f32_e32 v1, v10, v112
	v_mul_f32_e32 v1, 0xbfb8aa3b, v1
	v_exp_f32_e32 v1, v1
	v_add_f32_e32 v0, 1.0, v0
	v_rcp_f32_e32 v0, v0
	v_lshlrev_b32_e32 v10, 16, v115
	v_add_f32_e32 v1, 1.0, v1
	v_rcp_f32_e32 v1, v1
	v_mul_f32_e32 v0, v0, v132
	v_mul_f32_e32 v0, 0x3fb8aa3b, v0
	v_exp_f32_e32 v25, v0
	v_mul_f32_e32 v115, v110, v134
	v_mul_f32_e32 v114, v137, v115
	v_lshlrev_b32_e32 v26, 16, v117
	v_fma_f32 v0, -v25, v25, 1.0
; DI u16 f2bf(float f) { return (u16)(pack2(f, 0.f) & 0xffffu); }
; DI float bf2f(u16 h) { return __uint_as_float(((uint32_t)h) << 16); }
; DI int launder(int v) { asm volatile("" : "+v"(v)); return v; }
; template <int M> DI float shxf(float v) { return __int_as_float(shxi<M>(__float_as_int(v))); }
; DI float sigmoidf_(float x) { return __builtin_amdgcn_rcpf(1.f + __expf(-x)); }
; template <bool FINAL>
; DI void lru_item(int ws, PP p, char* shm, int item) {
;     ...
;     for (int mb = 0; mb < 2; ++mb)
; #pragma unroll
;       for (int i = 0; i < 16; ++i) {
;         const int tok = mb * 32 + hh * 4 + (i & 3) + 8 * (i >> 2);
;         const float xc = bf2f(XC[tok * KVS + j]);
;         const float r = sigmoidf_(ar[mb][i] + baj), ig = sigmoidf_(ai[mb][i] + bxj);
;         const float aa = __expf(r * la);
;         ar[mb][i] = aa;
;         ai[mb][i] = __builtin_amdgcn_sqrtf(__builtin_fmaf(-aa, aa, 1.f)) * ig * xc;
;       }
;     ...
; #pragma unroll
;     for (int mb = 0; mb < 2; ++mb)
; #pragma unroll
;       for (int q = 0; q < 4; ++q) {
;         float P = 1.f, H = 0.f;
; #pragma unroll
;         for (int e = 0; e < 4; ++e) {
;           const int idx = 4 * q + e;
;           H = ar[mb][idx] * H + ai[mb][idx];
;           P *= ar[mb][idx];
;           ar[mb][idx] = P;
;           ai[mb][idx] = H;
;         }
;         const float Po = shxf<32>(P), Ho = shxf<32>(H);
;         const float A0 = hh ? Po : P, B0 = hh ? Ho : H, A1 = hh ? P : Po, B1 = hh ? H : Ho;
;         const float mid = B0 + A0 * carry;
;         const float cin = hh ? mid : carry;
;         carry = B1 + A1 * mid;
;         atot *= A0 * A1;
;         if (FINAL) {
;           const int tl0 = launder(hh * 4);
; #pragma unroll
;           for (int e = 0; e < 4; ++e) {
;             const int idx = 4 * q + e;
;             const int tok = mb * 32 + tl0 + e + 8 * q;
;             const float hv = ai[mb][idx] + ar[mb][idx] * cin;
;             const long trow = (long)b * SEQ + t0 + tok;
;             const float g = bf2f(u[trow * IN0 + 512 + chj]);
;             wt16(p->h + trow * DM + chj, f2bf(hv * gelu_tanh(g)));
	v_sqrt_f32_e32 v0, v0
	s_nop 0
	v_mul_f32_e32 v32, v1, v0
	v_add_f32_e32 v0, v27, v111
	v_mul_f32_e32 v0, 0xbfb8aa3b, v0
	v_exp_f32_e32 v0, v0
	v_add_f32_e32 v1, v11, v112
	v_mul_f32_e32 v1, 0xbfb8aa3b, v1
	v_exp_f32_e32 v1, v1
	v_add_f32_e32 v0, 1.0, v0
	v_rcp_f32_e32 v0, v0
	v_add_f32_e32 v1, 1.0, v1
	v_rcp_f32_e32 v1, v1
	v_mul_f32_e32 v0, v0, v132
	v_mul_f32_e32 v0, 0x3fb8aa3b, v0
	v_exp_f32_e32 v27, v0
	s_nop 0
	v_fma_f32 v0, -v27, v27, 1.0
	v_sqrt_f32_e32 v0, v0
	s_nop 0
	v_mul_f32_e32 v33, v1, v0
	v_add_f32_e32 v1, v28, v111
	v_mul_f32_e32 v1, 0xbfb8aa3b, v1
	v_exp_f32_e32 v1, v1
	v_lshlrev_b32_e32 v0, 16, v116
	v_add_f32_e32 v1, 1.0, v1
	v_rcp_f32_e32 v1, v1
	s_nop 0
	v_mul_f32_e32 v1, v1, v132
	v_mul_f32_e32 v1, 0x3fb8aa3b, v1
	v_exp_f32_e32 v9, v1
	s_nop 0
	v_fma_f32 v1, -v9, v9, 1.0
	v_sqrt_f32_e32 v1, v1
	s_nop 0
	v_mul_f32_e32 v1, v2, v1
	v_mul_f32_e32 v8, v1, v0
	v_add_f32_e32 v0, v29, v111
	v_mul_f32_e32 v0, 0xbfb8aa3b, v0
	v_exp_f32_e32 v0, v0
	v_add_f32_e32 v1, v13, v112
	v_mul_f32_e32 v1, 0xbfb8aa3b, v1
	v_exp_f32_e32 v1, v1
	v_add_f32_e32 v0, 1.0, v0
	v_rcp_f32_e32 v0, v0
	v_fmac_f32_e32 v8, 0, v9
	v_add_f32_e32 v1, 1.0, v1
	v_rcp_f32_e32 v1, v1
	v_mul_f32_e32 v0, v0, v132
	v_mul_f32_e32 v0, 0x3fb8aa3b, v0
	v_exp_f32_e32 v11, v0
	s_nop 0
	v_fma_f32 v0, -v11, v11, 1.0
	v_sqrt_f32_e32 v0, v0
	s_nop 0
	v_mul_f32_e32 v13, v1, v0
	v_add_f32_e32 v0, v30, v111
	v_mul_f32_e32 v0, 0xbfb8aa3b, v0
	v_exp_f32_e32 v0, v0
	v_add_f32_e32 v1, v14, v112
	v_mul_f32_e32 v1, 0xbfb8aa3b, v1
	v_exp_f32_e32 v1, v1
	v_add_f32_e32 v0, 1.0, v0
	v_rcp_f32_e32 v0, v0
	v_add_f32_e32 v1, 1.0, v1
	v_rcp_f32_e32 v1, v1
	v_mul_f32_e32 v0, v0, v132
	v_mul_f32_e32 v0, 0x3fb8aa3b, v0
	v_exp_f32_e32 v14, v0
	s_nop 0
	v_fma_f32 v0, -v14, v14, 1.0
	v_sqrt_f32_e32 v0, v0
	s_nop 0
	v_mul_f32_e32 v17, v1, v0
	v_add_f32_e32 v0, v31, v111
	v_mul_f32_e32 v0, 0xbfb8aa3b, v0
	v_exp_f32_e32 v0, v0
	v_add_f32_e32 v1, v15, v112
	v_mul_f32_e32 v1, 0xbfb8aa3b, v1
	v_exp_f32_e32 v1, v1
	v_add_f32_e32 v0, 1.0, v0
	v_rcp_f32_e32 v0, v0
	v_mul_f32_e32 v112, v137, v113
	v_add_f32_e32 v1, 1.0, v1
	v_rcp_f32_e32 v1, v1
	v_mul_f32_e32 v0, v0, v132
	v_mul_f32_e32 v0, 0x3fb8aa3b, v0
	v_exp_f32_e32 v15, v0
	v_fmac_f32_e32 v112, v138, v135
	v_mul_f32_e32 v111, v140, v114
	v_mul_f32_e32 v28, v140, v112
	v_fma_f32 v0, -v15, v15, 1.0
	v_sqrt_f32_e32 v0, v0
	v_fmac_f32_e32 v28, v141, v139
	v_mov_b32_e32 v2, v28
	v_mul_f32_e32 v18, v1, v0
	v_mov_b32_e32 v0, v111
	v_mov_b32_e32 v1, v111
	s_nop 1
	v_permlane32_swap_b32_e32 v0, v1
	v_xor_b32_e32 v0, v1, v0
	v_mov_b32_e32 v1, v28
	s_nop 1
	v_permlane32_swap_b32_e32 v1, v2
	v_xor_b32_e32 v1, v2, v1
	v_xor_b32_e32 v0, v0, v111
	v_xor_b32_e32 v29, v1, v28
	v_cndmask_b32_e64 v1, v0, v111, s[10:11]
	v_cndmask_b32_e64 v30, v29, v28, s[10:11]
	v_lshlrev_b64 v[2:3], 1, v[70:71]
	v_lshl_add_u64 v[70:71], s[34:35], 0, v[6:7]
	v_cndmask_b32_e64 v31, v111, v0, s[10:11]
	v_fmac_f32_e32 v30, v73, v1
	s_waitcnt lgkmcnt(0)
	v_lshl_add_u64 v[0:1], s[0:1], 0, v[2:3]
	v_mad_u64_u32 v[116:117], s[0:1], v70, s52, v[4:5]
	v_mad_i32_i24 v117, v71, s52, v117
	v_lshl_add_u64 v[116:117], v[116:117], 0, v[2:3]
	s_mov_b32 s98, 0x1400
	s_mov_b32 s99, 0
	s_mov_b32 s100, 0x6400
	s_mov_b32 s101, 0
	global_load_ushort v196, v[116:117], off offset:1024
	v_lshl_add_u64 v[228:229], v[116:117], 0, s[98:99]
	global_load_ushort v197, v[228:229], off offset:1024
	v_lshl_add_u64 v[228:229], v[228:229], 0, s[98:99]
	global_load_ushort v198, v[228:229], off offset:1024
	v_lshl_add_u64 v[228:229], v[228:229], 0, s[98:99]
	global_load_ushort v199, v[228:229], off offset:1024
	v_lshl_add_u64 v[228:229], v[228:229], 0, s[100:101]
	global_load_ushort v200, v[228:229], off offset:1024
	v_lshl_add_u64 v[228:229], v[228:229], 0, s[98:99]
	global_load_ushort v201, v[228:229], off offset:1024
	v_lshl_add_u64 v[228:229], v[228:229], 0, s[98:99]
	global_load_ushort v202, v[228:229], off offset:1024
	v_lshl_add_u64 v[228:229], v[228:229], 0, s[98:99]
	global_load_ushort v203, v[228:229], off offset:1024
	v_lshl_add_u64 v[228:229], v[228:229], 0, s[100:101]
	global_load_ushort v204, v[228:229], off offset:1024
	v_lshl_add_u64 v[228:229], v[228:229], 0, s[98:99]
	global_load_ushort v205, v[228:229], off offset:1024
	v_lshl_add_u64 v[228:229], v[228:229], 0, s[98:99]
	global_load_ushort v206, v[228:229], off offset:1024
	v_lshl_add_u64 v[228:229], v[228:229], 0, s[98:99]
	global_load_ushort v207, v[228:229], off offset:1024
	v_lshl_add_u64 v[228:229], v[228:229], 0, s[100:101]
	global_load_ushort v208, v[228:229], off offset:1024
	v_lshl_add_u64 v[228:229], v[228:229], 0, s[98:99]
	global_load_ushort v209, v[228:229], off offset:1024
	v_lshl_add_u64 v[228:229], v[228:229], 0, s[98:99]
	global_load_ushort v210, v[228:229], off offset:1024
	v_lshl_add_u64 v[228:229], v[228:229], 0, s[98:99]
	global_load_ushort v211, v[228:229], off offset:1024
	v_lshl_add_u64 v[228:229], v[228:229], 0, s[100:101]
	global_load_ushort v212, v[228:229], off offset:1024
	v_lshl_add_u64 v[228:229], v[228:229], 0, s[98:99]
	global_load_ushort v213, v[228:229], off offset:1024
	v_lshl_add_u64 v[228:229], v[228:229], 0, s[98:99]
	global_load_ushort v214, v[228:229], off offset:1024
	v_lshl_add_u64 v[228:229], v[228:229], 0, s[98:99]
	global_load_ushort v215, v[228:229], off offset:1024
	v_lshl_add_u64 v[228:229], v[228:229], 0, s[100:101]
	global_load_ushort v216, v[228:229], off offset:1024
	v_lshl_add_u64 v[228:229], v[228:229], 0, s[98:99]
	global_load_ushort v217, v[228:229], off offset:1024
	v_lshl_add_u64 v[228:229], v[228:229], 0, s[98:99]
	global_load_ushort v218, v[228:229], off offset:1024
	v_lshl_add_u64 v[228:229], v[228:229], 0, s[98:99]
	global_load_ushort v219, v[228:229], off offset:1024
	v_lshl_add_u64 v[228:229], v[228:229], 0, s[100:101]
	global_load_ushort v220, v[228:229], off offset:1024
	v_lshl_add_u64 v[228:229], v[228:229], 0, s[98:99]
	global_load_ushort v221, v[228:229], off offset:1024
	v_lshl_add_u64 v[228:229], v[228:229], 0, s[98:99]
	global_load_ushort v222, v[228:229], off offset:1024
	v_lshl_add_u64 v[228:229], v[228:229], 0, s[98:99]
	global_load_ushort v223, v[228:229], off offset:1024
	v_lshl_add_u64 v[228:229], v[228:229], 0, s[100:101]
	global_load_ushort v224, v[228:229], off offset:1024
	v_lshl_add_u64 v[228:229], v[228:229], 0, s[98:99]
	global_load_ushort v225, v[228:229], off offset:1024
	v_lshl_add_u64 v[228:229], v[228:229], 0, s[98:99]
	global_load_ushort v226, v[228:229], off offset:1024
	v_lshl_add_u64 v[228:229], v[228:229], 0, s[98:99]
	global_load_ushort v227, v[228:229], off offset:1024
	v_cndmask_b32_e64 v73, v30, v73, s[10:11]
	v_fmac_f32_e32 v109, v110, v73
	v_lshlrev_b64 v[70:71], 11, v[70:71]
	v_lshl_add_u64 v[70:71], v[0:1], 0, v[70:71]
	v_fmac_f32_e32 v113, v115, v73
	v_fmac_f32_e32 v112, v114, v73
	v_fma_f32 v73, v111, v73, v28
	s_waitcnt vmcnt(0)
; DI u16 f2bf(float f) { return (u16)(pack2(f, 0.f) & 0xffffu); }
; DI float bf2f(u16 h) { return __uint_as_float(((uint32_t)h) << 16); }
; DI int launder(int v) { asm volatile("" : "+v"(v)); return v; }
; template <int M> DI float shxf(float v) { return __int_as_float(shxi<M>(__float_as_int(v))); }
; DI float gelu_tanh(float x) {
;   const float z = 0.7978845608028654f * (x + 0.044715f * x * x * x);
;   const float th = 1.f - 2.f * __builtin_amdgcn_rcpf(1.f + __expf(2.f * z));
;   return 0.5f * x * (1.f + th);
; }
; template <bool FINAL>
; DI void lru_item(int ws, PP p, char* shm, int item) {
;     ...
; #pragma unroll
;     for (int mb = 0; mb < 2; ++mb)
; #pragma unroll
;       for (int q = 0; q < 4; ++q) {
;         float P = 1.f, H = 0.f;
; #pragma unroll
;         for (int e = 0; e < 4; ++e) {
;           const int idx = 4 * q + e;
;           H = ar[mb][idx] * H + ai[mb][idx];
;           P *= ar[mb][idx];
;           ar[mb][idx] = P;
;           ai[mb][idx] = H;
;         }
;         const float Po = shxf<32>(P), Ho = shxf<32>(H);
;         const float A0 = hh ? Po : P, B0 = hh ? Ho : H, A1 = hh ? P : Po, B1 = hh ? H : Ho;
;         const float mid = B0 + A0 * carry;
;         const float cin = hh ? mid : carry;
;         carry = B1 + A1 * mid;
;         atot *= A0 * A1;
;         if (FINAL) {
;           const int tl0 = launder(hh * 4);
; #pragma unroll
;           for (int e = 0; e < 4; ++e) {
;             const int idx = 4 * q + e;
;             const int tok = mb * 32 + tl0 + e + 8 * q;
;             const float hv = ai[mb][idx] + ar[mb][idx] * cin;
;             const long trow = (long)b * SEQ + t0 + tok;
;             const float g = bf2f(u[trow * IN0 + 512 + chj]);
;             wt16(p->h + trow * DM + chj, f2bf(hv * gelu_tanh(g)));
;           }
;         }
	v_mov_b32_e32 v7, v196
	v_lshlrev_b32_e32 v7, 16, v7
	v_mul_f32_e32 v110, 0x3d372713, v7
	v_mul_f32_e32 v110, v110, v7
	v_fma_f32 v110, v110, v7, v7
	v_mul_f32_e32 v110, 0x3f4c422a, v110
	v_add_f32_e32 v110, v110, v110
	v_mul_f32_e32 v110, 0x3fb8aa3b, v110
	v_exp_f32_e32 v110, v110
	v_mul_f32_e32 v7, 0.5, v7
	v_add_f32_e32 v110, 1.0, v110
	v_rcp_f32_e32 v110, v110
	s_nop 0
	v_fma_f32 v110, v110, -2.0, 1.0
	v_add_f32_e32 v110, 1.0, v110
	v_mul_f32_e32 v7, v7, v110
	v_mul_f32_e32 v7, v109, v7
	v_cvt_pk_bf16_f32 v7, v7, s0
	global_store_short v[70:71], v7, off
	v_add_u32_e32 v70, 1, v6
	v_ashrrev_i32_e32 v71, 31, v70
	v_lshl_add_u64 v[70:71], s[34:35], 0, v[70:71]
	v_mad_u64_u32 v[116:117], s[0:1], v70, s52, v[4:5]
	v_mad_i32_i24 v117, v71, s52, v117
	v_lshl_add_u64 v[116:117], v[116:117], 0, v[2:3]
	v_mov_b32_e32 v7, v197
	v_lshlrev_b64 v[70:71], 11, v[70:71]
	v_lshl_add_u64 v[70:71], v[0:1], 0, v[70:71]
	s_nop 0
	v_lshlrev_b32_e32 v7, 16, v7
	v_mul_f32_e32 v109, 0x3d372713, v7
	v_mul_f32_e32 v109, v109, v7
	v_fma_f32 v109, v109, v7, v7
	v_mul_f32_e32 v109, 0x3f4c422a, v109
	v_add_f32_e32 v109, v109, v109
	v_mul_f32_e32 v109, 0x3fb8aa3b, v109
	v_exp_f32_e32 v109, v109
	v_mul_f32_e32 v7, 0.5, v7
	v_add_f32_e32 v109, 1.0, v109
	v_rcp_f32_e32 v109, v109
	s_nop 0
	v_fma_f32 v109, v109, -2.0, 1.0
	v_add_f32_e32 v109, 1.0, v109
	v_mul_f32_e32 v7, v7, v109
	v_mul_f32_e32 v7, v113, v7
	v_cvt_pk_bf16_f32 v7, v7, s0
	global_store_short v[70:71], v7, off
	v_add_u32_e32 v70, 2, v6
	v_ashrrev_i32_e32 v71, 31, v70
	v_lshl_add_u64 v[70:71], s[34:35], 0, v[70:71]
	v_mad_u64_u32 v[114:115], s[0:1], v70, s52, v[4:5]
	v_mad_i32_i24 v115, v71, s52, v115
	v_lshl_add_u64 v[114:115], v[114:115], 0, v[2:3]
	v_mov_b32_e32 v7, v198
	v_lshlrev_b64 v[70:71], 11, v[70:71]
	v_lshl_add_u64 v[70:71], v[0:1], 0, v[70:71]
	v_add_u32_e32 v6, 3, v6
	s_nop 0
	v_lshlrev_b32_e32 v7, 16, v7
	v_mul_f32_e32 v109, 0x3d372713, v7
	v_mul_f32_e32 v109, v109, v7
	v_fma_f32 v109, v109, v7, v7
	v_mul_f32_e32 v109, 0x3f4c422a, v109
	v_add_f32_e32 v109, v109, v109
	v_mul_f32_e32 v109, 0x3fb8aa3b, v109
	v_exp_f32_e32 v109, v109
	v_mul_f32_e32 v7, 0.5, v7
	v_add_f32_e32 v109, 1.0, v109
	v_rcp_f32_e32 v109, v109
	s_nop 0
	v_fma_f32 v109, v109, -2.0, 1.0
	v_add_f32_e32 v109, 1.0, v109
	v_mul_f32_e32 v7, v7, v109
	v_mul_f32_e32 v7, v112, v7
	v_cvt_pk_bf16_f32 v7, v7, s0
	global_store_short v[70:71], v7, off
	v_ashrrev_i32_e32 v7, 31, v6
	v_lshl_add_u64 v[6:7], s[34:35], 0, v[6:7]
	v_mad_u64_u32 v[70:71], s[0:1], v6, s52, v[4:5]
	v_mad_i32_i24 v71, v7, s52, v71
	v_lshl_add_u64 v[70:71], v[70:71], 0, v[2:3]
	v_mov_b32_e32 v70, v199
	v_mul_f32_e32 v109, v101, v98
	v_lshlrev_b64 v[6:7], 11, v[6:7]
	v_fmac_f32_e32 v109, v103, v100
	v_mul_f32_e32 v100, v99, v101
	v_lshl_add_u64 v[6:7], v[0:1], 0, v[6:7]
	s_nop 0
	v_lshlrev_b32_e32 v70, 16, v70
	v_mul_f32_e32 v71, 0x3d372713, v70
	v_mul_f32_e32 v71, v71, v70
	v_fma_f32 v71, v71, v70, v70
	v_mul_f32_e32 v71, 0x3f4c422a, v71
	v_add_f32_e32 v71, v71, v71
	v_mul_f32_e32 v71, 0x3fb8aa3b, v71
	v_exp_f32_e32 v71, v71
	v_mul_f32_e32 v70, 0.5, v70
	v_add_f32_e32 v71, 1.0, v71
	v_rcp_f32_e32 v71, v71
	s_nop 0
	v_fma_f32 v71, v71, -2.0, 1.0
	v_add_f32_e32 v71, 1.0, v71
	v_mul_f32_e32 v70, v70, v71
	v_mul_f32_e32 v70, v73, v70
	v_cvt_pk_bf16_f32 v70, v70, s0
	v_cndmask_b32_e64 v73, v28, v29, s[10:11]
	v_mul_f32_e32 v71, v104, v100
	global_store_short v[6:7], v70, off
	v_fmac_f32_e32 v73, v31, v30
	v_mul_f32_e32 v70, v104, v109
	v_mul_f32_e32 v30, v107, v71
	v_fmac_f32_e32 v70, v106, v102
	v_mov_b32_e32 v7, v30
	v_mov_b32_e32 v28, v30
	v_mul_f32_e32 v6, v107, v70
	s_nop 0
	v_permlane32_swap_b32_e32 v7, v28
	v_fmac_f32_e32 v6, v108, v105
	v_xor_b32_e32 v7, v28, v7
	v_xor_b32_e32 v29, v7, v30
	v_mov_b32_e32 v7, v6
	v_mov_b32_e32 v28, v6
	s_nop 1
	v_permlane32_swap_b32_e32 v7, v28
	v_xor_b32_e32 v7, v28, v7
	v_xor_b32_e32 v7, v7, v6
	v_cndmask_b32_e64 v31, v29, v30, s[10:11]
	v_cndmask_b32_e64 v28, v7, v6, s[10:11]
	v_fmac_f32_e32 v28, v73, v31
	v_cndmask_b32_e64 v31, v28, v73, s[10:11]
	v_mov_b32_e32 v73, v86
	v_fmac_f32_e32 v98, v99, v31
	v_add_u32_e32 v102, 8, v73
	v_ashrrev_i32_e32 v103, 31, v102
	v_lshl_add_u64 v[102:103], s[34:35], 0, v[102:103]
	v_mad_u64_u32 v[104:105], s[0:1], v102, s52, v[4:5]
	v_mad_i32_i24 v105, v103, s52, v105
	v_lshl_add_u64 v[104:105], v[104:105], 0, v[2:3]
	v_mov_b32_e32 v99, v200
	v_lshlrev_b64 v[102:103], 11, v[102:103]
	v_lshl_add_u64 v[102:103], v[0:1], 0, v[102:103]
	v_fmac_f32_e32 v109, v100, v31
	v_fmac_f32_e32 v70, v71, v31
	v_cndmask_b32_e64 v29, v30, v29, s[10:11]
	s_nop 0
	v_lshlrev_b32_e32 v99, 16, v99
	v_mul_f32_e32 v101, 0x3d372713, v99
	v_mul_f32_e32 v101, v101, v99
	v_fma_f32 v101, v101, v99, v99
	v_mul_f32_e32 v101, 0x3f4c422a, v101
	v_add_f32_e32 v101, v101, v101
	v_mul_f32_e32 v101, 0x3fb8aa3b, v101
	v_exp_f32_e32 v101, v101
	v_mul_f32_e32 v99, 0.5, v99
	v_add_f32_e32 v101, 1.0, v101
	v_rcp_f32_e32 v101, v101
	s_nop 0
	v_fma_f32 v101, v101, -2.0, 1.0
	v_add_f32_e32 v101, 1.0, v101
	v_mul_f32_e32 v99, v99, v101
	v_mul_f32_e32 v98, v98, v99
	v_cvt_pk_bf16_f32 v98, v98, s0
	global_store_short v[102:103], v98, off
	v_add_u32_e32 v98, 9, v73
	v_ashrrev_i32_e32 v99, 31, v98
	v_lshl_add_u64 v[98:99], s[34:35], 0, v[98:99]
	v_mad_u64_u32 v[100:101], s[0:1], v98, s52, v[4:5]
	v_mad_i32_i24 v101, v99, s52, v101
	v_lshl_add_u64 v[100:101], v[100:101], 0, v[2:3]
	v_mov_b32_e32 v100, v201
	v_lshlrev_b64 v[98:99], 11, v[98:99]
	v_lshl_add_u64 v[98:99], v[0:1], 0, v[98:99]
	s_nop 0
	v_lshlrev_b32_e32 v100, 16, v100
	v_mul_f32_e32 v101, 0x3d372713, v100
	v_mul_f32_e32 v101, v101, v100
	v_fma_f32 v101, v101, v100, v100
; DI u16 f2bf(float f) { return (u16)(pack2(f, 0.f) & 0xffffu); }
; DI float bf2f(u16 h) { return __uint_as_float(((uint32_t)h) << 16); }
; DI int launder(int v) { asm volatile("" : "+v"(v)); return v; }
; template <int M> DI float shxf(float v) { return __int_as_float(shxi<M>(__float_as_int(v))); }
; DI float gelu_tanh(float x) {
;   const float z = 0.7978845608028654f * (x + 0.044715f * x * x * x);
;   const float th = 1.f - 2.f * __builtin_amdgcn_rcpf(1.f + __expf(2.f * z));
;   return 0.5f * x * (1.f + th);
; }
; template <bool FINAL>
; DI void lru_item(int ws, PP p, char* shm, int item) {
;     ...
; #pragma unroll
;     for (int mb = 0; mb < 2; ++mb)
; #pragma unroll
;       for (int q = 0; q < 4; ++q) {
;         float P = 1.f, H = 0.f;
; #pragma unroll
;         for (int e = 0; e < 4; ++e) {
;           const int idx = 4 * q + e;
;           H = ar[mb][idx] * H + ai[mb][idx];
;           P *= ar[mb][idx];
;           ar[mb][idx] = P;
;           ai[mb][idx] = H;
;         }
;         const float Po = shxf<32>(P), Ho = shxf<32>(H);
;         const float A0 = hh ? Po : P, B0 = hh ? Ho : H, A1 = hh ? P : Po, B1 = hh ? H : Ho;
;         const float mid = B0 + A0 * carry;
;         const float cin = hh ? mid : carry;
;         carry = B1 + A1 * mid;
;         atot *= A0 * A1;
;         if (FINAL) {
;           const int tl0 = launder(hh * 4);
; #pragma unroll
;           for (int e = 0; e < 4; ++e) {
;             const int idx = 4 * q + e;
;             const int tok = mb * 32 + tl0 + e + 8 * q;
;             const float hv = ai[mb][idx] + ar[mb][idx] * cin;
;             const long trow = (long)b * SEQ + t0 + tok;
;             const float g = bf2f(u[trow * IN0 + 512 + chj]);
;             wt16(p->h + trow * DM + chj, f2bf(hv * gelu_tanh(g)));
;           }
;         }
	v_mul_f32_e32 v101, 0x3f4c422a, v101
	v_add_f32_e32 v101, v101, v101
	v_mul_f32_e32 v101, 0x3fb8aa3b, v101
	v_exp_f32_e32 v101, v101
	v_mul_f32_e32 v100, 0.5, v100
	v_add_f32_e32 v101, 1.0, v101
	v_rcp_f32_e32 v101, v101
	s_nop 0
	v_fma_f32 v101, v101, -2.0, 1.0
	v_add_f32_e32 v101, 1.0, v101
	v_mul_f32_e32 v100, v100, v101
	v_mul_f32_e32 v100, v109, v100
	v_cvt_pk_bf16_f32 v100, v100, s0
	global_store_short v[98:99], v100, off
	v_add_u32_e32 v98, 10, v73
	v_ashrrev_i32_e32 v99, 31, v98
	v_lshl_add_u64 v[98:99], s[34:35], 0, v[98:99]
	v_mad_u64_u32 v[100:101], s[0:1], v98, s52, v[4:5]
	v_mad_i32_i24 v101, v99, s52, v101
	v_lshl_add_u64 v[100:101], v[100:101], 0, v[2:3]
	v_mov_b32_e32 v71, v202
	v_lshlrev_b64 v[98:99], 11, v[98:99]
	v_lshl_add_u64 v[98:99], v[0:1], 0, v[98:99]
	s_nop 0
	v_lshlrev_b32_e32 v71, 16, v71
	v_mul_f32_e32 v100, 0x3d372713, v71
	v_mul_f32_e32 v100, v100, v71
	v_fma_f32 v100, v100, v71, v71
	v_mul_f32_e32 v100, 0x3f4c422a, v100
	v_add_f32_e32 v100, v100, v100
	v_mul_f32_e32 v100, 0x3fb8aa3b, v100
	v_exp_f32_e32 v100, v100
	v_mul_f32_e32 v71, 0.5, v71
	v_add_f32_e32 v100, 1.0, v100
	v_rcp_f32_e32 v100, v100
	s_nop 0
	v_fma_f32 v100, v100, -2.0, 1.0
	v_add_f32_e32 v100, 1.0, v100
	v_mul_f32_e32 v71, v71, v100
	v_mul_f32_e32 v70, v70, v71
	v_cvt_pk_bf16_f32 v70, v70, s0
	global_store_short v[98:99], v70, off
	v_add_u32_e32 v70, 11, v73
	v_ashrrev_i32_e32 v71, 31, v70
	v_fma_f32 v73, v30, v31, v6
	v_lshl_add_u64 v[30:31], s[34:35], 0, v[70:71]
	v_mad_u64_u32 v[70:71], s[0:1], v30, s52, v[4:5]
	v_mad_i32_i24 v71, v31, s52, v71
	v_lshl_add_u64 v[70:71], v[70:71], 0, v[2:3]
	v_mov_b32_e32 v70, v203
	v_mul_f32_e32 v98, v90, v75
	v_lshlrev_b64 v[30:31], 11, v[30:31]
	v_fmac_f32_e32 v98, v92, v77
	v_mul_f32_e32 v77, v76, v90
	v_lshl_add_u64 v[30:31], v[0:1], 0, v[30:31]
	s_nop 0
	v_lshlrev_b32_e32 v70, 16, v70
	v_mul_f32_e32 v71, 0x3d372713, v70
	v_mul_f32_e32 v71, v71, v70
	v_fma_f32 v71, v71, v70, v70
	v_mul_f32_e32 v71, 0x3f4c422a, v71
	v_add_f32_e32 v71, v71, v71
	v_mul_f32_e32 v71, 0x3fb8aa3b, v71
	v_exp_f32_e32 v71, v71
	v_mul_f32_e32 v70, 0.5, v70
	v_add_f32_e32 v71, 1.0, v71
	v_rcp_f32_e32 v71, v71
	s_nop 0
	v_fma_f32 v71, v71, -2.0, 1.0
	v_add_f32_e32 v71, 1.0, v71
	v_mul_f32_e32 v70, v70, v71
	v_mul_f32_e32 v70, v73, v70
	v_cvt_pk_bf16_f32 v70, v70, s0
	v_mul_f32_e32 v71, v93, v77
	global_store_short v[30:31], v70, off
	v_cndmask_b32_e64 v31, v6, v7, s[10:11]
	v_mul_f32_e32 v70, v93, v98
	v_mul_f32_e32 v30, v96, v71
	v_fmac_f32_e32 v31, v29, v28
	v_fmac_f32_e32 v70, v95, v91
	v_mov_b32_e32 v7, v30
	v_mov_b32_e32 v28, v30
	v_mul_f32_e32 v6, v96, v70
	s_nop 0
	v_permlane32_swap_b32_e32 v7, v28
	v_fmac_f32_e32 v6, v97, v94
	v_xor_b32_e32 v7, v28, v7
	v_xor_b32_e32 v29, v7, v30
	v_mov_b32_e32 v7, v6
	v_mov_b32_e32 v28, v6
	s_nop 1
	v_permlane32_swap_b32_e32 v7, v28
	v_xor_b32_e32 v7, v28, v7
	v_xor_b32_e32 v7, v7, v6
	v_cndmask_b32_e64 v73, v29, v30, s[10:11]
	v_cndmask_b32_e64 v28, v7, v6, s[10:11]
	v_fmac_f32_e32 v28, v31, v73
	v_mov_b32_e32 v73, v86
	v_cndmask_b32_e64 v31, v28, v31, s[10:11]
	v_add_u32_e32 v90, 16, v73
	v_ashrrev_i32_e32 v91, 31, v90
	v_lshl_add_u64 v[90:91], s[34:35], 0, v[90:91]
	v_mad_u64_u32 v[92:93], s[0:1], v90, s52, v[4:5]
	v_mad_i32_i24 v93, v91, s52, v93
	v_lshl_add_u64 v[92:93], v[92:93], 0, v[2:3]
	v_fmac_f32_e32 v75, v76, v31
	v_mov_b32_e32 v76, v204
	v_lshlrev_b64 v[90:91], 11, v[90:91]
	v_fmac_f32_e32 v98, v77, v31
	v_lshl_add_u64 v[90:91], v[0:1], 0, v[90:91]
	v_fmac_f32_e32 v70, v71, v31
	v_cndmask_b32_e64 v29, v30, v29, s[10:11]
	s_nop 0
	v_lshlrev_b32_e32 v76, 16, v76
	v_mul_f32_e32 v92, 0x3d372713, v76
	v_mul_f32_e32 v92, v92, v76
	v_fma_f32 v92, v92, v76, v76
	v_mul_f32_e32 v92, 0x3f4c422a, v92
	v_add_f32_e32 v92, v92, v92
	v_mul_f32_e32 v92, 0x3fb8aa3b, v92
	v_exp_f32_e32 v92, v92
	v_mul_f32_e32 v76, 0.5, v76
	v_add_f32_e32 v92, 1.0, v92
	v_rcp_f32_e32 v92, v92
	s_nop 0
	v_fma_f32 v92, v92, -2.0, 1.0
	v_add_f32_e32 v92, 1.0, v92
	v_mul_f32_e32 v76, v76, v92
	v_mul_f32_e32 v75, v75, v76
	v_add_u32_e32 v76, 17, v73
	v_ashrrev_i32_e32 v77, 31, v76
	v_cvt_pk_bf16_f32 v75, v75, s0
	v_lshl_add_u64 v[76:77], s[34:35], 0, v[76:77]
	global_store_short v[90:91], v75, off
	v_mad_u64_u32 v[90:91], s[0:1], v76, s52, v[4:5]
	v_mad_i32_i24 v91, v77, s52, v91
	v_lshl_add_u64 v[90:91], v[90:91], 0, v[2:3]
	v_mov_b32_e32 v75, v205
	v_lshlrev_b64 v[76:77], 11, v[76:77]
	v_lshl_add_u64 v[76:77], v[0:1], 0, v[76:77]
	s_nop 0
	v_lshlrev_b32_e32 v75, 16, v75
	v_mul_f32_e32 v90, 0x3d372713, v75
	v_mul_f32_e32 v90, v90, v75
	v_fma_f32 v90, v90, v75, v75
	v_mul_f32_e32 v90, 0x3f4c422a, v90
	v_add_f32_e32 v90, v90, v90
	v_mul_f32_e32 v90, 0x3fb8aa3b, v90
	v_exp_f32_e32 v90, v90
	v_mul_f32_e32 v75, 0.5, v75
	v_add_f32_e32 v90, 1.0, v90
	v_rcp_f32_e32 v90, v90
	s_nop 0
	v_fma_f32 v90, v90, -2.0, 1.0
	v_add_f32_e32 v90, 1.0, v90
	v_mul_f32_e32 v75, v75, v90
	v_mul_f32_e32 v75, v98, v75
	v_cvt_pk_bf16_f32 v75, v75, s0
	global_store_short v[76:77], v75, off
	v_add_u32_e32 v76, 18, v73
	v_ashrrev_i32_e32 v77, 31, v76
	v_lshl_add_u64 v[76:77], s[34:35], 0, v[76:77]
	v_mad_u64_u32 v[90:91], s[0:1], v76, s52, v[4:5]
	v_mad_i32_i24 v91, v77, s52, v91
	v_lshl_add_u64 v[90:91], v[90:91], 0, v[2:3]
	v_mov_b32_e32 v71, v206
	v_lshlrev_b64 v[76:77], 11, v[76:77]
	v_lshl_add_u64 v[76:77], v[0:1], 0, v[76:77]
	s_nop 0
	v_lshlrev_b32_e32 v71, 16, v71
	v_mul_f32_e32 v75, 0x3d372713, v71
	v_mul_f32_e32 v75, v75, v71
	v_fma_f32 v75, v75, v71, v71
	v_mul_f32_e32 v75, 0x3f4c422a, v75
	v_add_f32_e32 v75, v75, v75
	v_mul_f32_e32 v75, 0x3fb8aa3b, v75
	v_exp_f32_e32 v75, v75
	v_mul_f32_e32 v71, 0.5, v71
	v_add_f32_e32 v75, 1.0, v75
; DI u16 f2bf(float f) { return (u16)(pack2(f, 0.f) & 0xffffu); }
; DI float bf2f(u16 h) { return __uint_as_float(((uint32_t)h) << 16); }
; DI int launder(int v) { asm volatile("" : "+v"(v)); return v; }
; template <int M> DI float shxf(float v) { return __int_as_float(shxi<M>(__float_as_int(v))); }
; DI float gelu_tanh(float x) {
;   const float z = 0.7978845608028654f * (x + 0.044715f * x * x * x);
;   const float th = 1.f - 2.f * __builtin_amdgcn_rcpf(1.f + __expf(2.f * z));
;   return 0.5f * x * (1.f + th);
; }
; template <bool FINAL>
; DI void lru_item(int ws, PP p, char* shm, int item) {
;     ...
; #pragma unroll
;     for (int mb = 0; mb < 2; ++mb)
; #pragma unroll
;       for (int q = 0; q < 4; ++q) {
;         float P = 1.f, H = 0.f;
; #pragma unroll
;         for (int e = 0; e < 4; ++e) {
;           const int idx = 4 * q + e;
;           H = ar[mb][idx] * H + ai[mb][idx];
;           P *= ar[mb][idx];
;           ar[mb][idx] = P;
;           ai[mb][idx] = H;
;         }
;         const float Po = shxf<32>(P), Ho = shxf<32>(H);
;         const float A0 = hh ? Po : P, B0 = hh ? Ho : H, A1 = hh ? P : Po, B1 = hh ? H : Ho;
;         const float mid = B0 + A0 * carry;
;         const float cin = hh ? mid : carry;
;         carry = B1 + A1 * mid;
;         atot *= A0 * A1;
;         if (FINAL) {
;           const int tl0 = launder(hh * 4);
; #pragma unroll
;           for (int e = 0; e < 4; ++e) {
;             const int idx = 4 * q + e;
;             const int tok = mb * 32 + tl0 + e + 8 * q;
;             const float hv = ai[mb][idx] + ar[mb][idx] * cin;
;             const long trow = (long)b * SEQ + t0 + tok;
;             const float g = bf2f(u[trow * IN0 + 512 + chj]);
;             wt16(p->h + trow * DM + chj, f2bf(hv * gelu_tanh(g)));
;           }
;         }
	v_rcp_f32_e32 v75, v75
	s_nop 0
	v_fma_f32 v75, v75, -2.0, 1.0
	v_add_f32_e32 v75, 1.0, v75
	v_mul_f32_e32 v71, v71, v75
	v_mul_f32_e32 v70, v70, v71
	v_cvt_pk_bf16_f32 v70, v70, s0
	global_store_short v[76:77], v70, off
	v_add_u32_e32 v70, 19, v73
	v_ashrrev_i32_e32 v71, 31, v70
	v_fma_f32 v73, v30, v31, v6
	v_lshl_add_u64 v[30:31], s[34:35], 0, v[70:71]
	v_mad_u64_u32 v[70:71], s[0:1], v30, s52, v[4:5]
	v_mad_i32_i24 v71, v31, s52, v71
	v_lshl_add_u64 v[70:71], v[70:71], 0, v[2:3]
	v_mov_b32_e32 v70, v207
	v_lshlrev_b64 v[30:31], 11, v[30:31]
	v_lshl_add_u64 v[30:31], v[0:1], 0, v[30:31]
	s_nop 0
	v_lshlrev_b32_e32 v70, 16, v70
	v_mul_f32_e32 v71, 0x3d372713, v70
	v_mul_f32_e32 v71, v71, v70
	v_fma_f32 v71, v71, v70, v70
	v_mul_f32_e32 v71, 0x3f4c422a, v71
	v_add_f32_e32 v71, v71, v71
	v_mul_f32_e32 v71, 0x3fb8aa3b, v71
	v_exp_f32_e32 v71, v71
	v_mul_f32_e32 v70, 0.5, v70
	v_add_f32_e32 v71, 1.0, v71
	v_rcp_f32_e32 v71, v71
	s_nop 0
	v_fma_f32 v71, v71, -2.0, 1.0
	v_add_f32_e32 v71, 1.0, v71
	v_mul_f32_e32 v70, v70, v71
	v_mul_f32_e32 v70, v73, v70
	v_cvt_pk_bf16_f32 v70, v70, s0
	global_store_short v[30:31], v70, off
	v_mul_f32_e32 v70, v59, v56
	v_fmac_f32_e32 v70, v61, v58
	v_mul_f32_e32 v61, v57, v59
	v_mul_f32_e32 v59, v62, v61
	v_cndmask_b32_e64 v31, v6, v7, s[10:11]
	v_mul_f32_e32 v58, v62, v70
	v_mul_f32_e32 v30, v63, v59
	v_fmac_f32_e32 v31, v29, v28
	v_fmac_f32_e32 v58, v72, v60
	v_mov_b32_e32 v7, v30
	v_mov_b32_e32 v28, v30
	v_mul_f32_e32 v6, v63, v58
	s_nop 0
	v_permlane32_swap_b32_e32 v7, v28
	v_fmac_f32_e32 v6, v74, v64
	v_xor_b32_e32 v7, v28, v7
	v_xor_b32_e32 v29, v7, v30
	v_mov_b32_e32 v7, v6
	v_mov_b32_e32 v28, v6
	s_nop 1
	v_permlane32_swap_b32_e32 v7, v28
	v_xor_b32_e32 v7, v28, v7
	v_xor_b32_e32 v7, v7, v6
	v_cndmask_b32_e64 v60, v29, v30, s[10:11]
	v_cndmask_b32_e64 v28, v7, v6, s[10:11]
	v_fmac_f32_e32 v28, v31, v60
	v_mov_b32_e32 v60, v86
	v_cndmask_b32_e64 v31, v28, v31, s[10:11]
	v_add_u32_e32 v62, 24, v60
	v_ashrrev_i32_e32 v63, 31, v62
	v_lshl_add_u64 v[62:63], s[34:35], 0, v[62:63]
	v_mad_u64_u32 v[72:73], s[0:1], v62, s52, v[4:5]
	v_mad_i32_i24 v73, v63, s52, v73
	v_lshl_add_u64 v[72:73], v[72:73], 0, v[2:3]
	v_fmac_f32_e32 v56, v57, v31
	v_mov_b32_e32 v57, v208
	v_lshlrev_b64 v[62:63], 11, v[62:63]
	v_lshl_add_u64 v[62:63], v[0:1], 0, v[62:63]
	v_fmac_f32_e32 v70, v61, v31
	v_fmac_f32_e32 v58, v59, v31
	v_cndmask_b32_e64 v29, v30, v29, s[10:11]
	s_nop 0
	v_lshlrev_b32_e32 v57, 16, v57
	v_mul_f32_e32 v64, 0x3d372713, v57
	v_mul_f32_e32 v64, v64, v57
	v_fma_f32 v64, v64, v57, v57
	v_mul_f32_e32 v64, 0x3f4c422a, v64
	v_add_f32_e32 v64, v64, v64
	v_mul_f32_e32 v64, 0x3fb8aa3b, v64
	v_exp_f32_e32 v64, v64
	v_mul_f32_e32 v57, 0.5, v57
	v_add_f32_e32 v64, 1.0, v64
	v_rcp_f32_e32 v64, v64
	s_nop 0
	v_fma_f32 v64, v64, -2.0, 1.0
	v_add_f32_e32 v64, 1.0, v64
	v_mul_f32_e32 v57, v57, v64
	v_mul_f32_e32 v56, v56, v57
	v_cvt_pk_bf16_f32 v56, v56, s0
	global_store_short v[62:63], v56, off
	v_add_u32_e32 v56, 25, v60
	v_ashrrev_i32_e32 v57, 31, v56
	v_lshl_add_u64 v[56:57], s[34:35], 0, v[56:57]
	v_mad_u64_u32 v[62:63], s[0:1], v56, s52, v[4:5]
	v_mad_i32_i24 v63, v57, s52, v63
	v_lshl_add_u64 v[62:63], v[62:63], 0, v[2:3]
	v_mov_b32_e32 v61, v209
	v_lshlrev_b64 v[56:57], 11, v[56:57]
	v_lshl_add_u64 v[56:57], v[0:1], 0, v[56:57]
	s_nop 0
	v_lshlrev_b32_e32 v61, 16, v61
	v_mul_f32_e32 v62, 0x3d372713, v61
	v_mul_f32_e32 v62, v62, v61
	v_fma_f32 v62, v62, v61, v61
	v_mul_f32_e32 v62, 0x3f4c422a, v62
	v_add_f32_e32 v62, v62, v62
	v_mul_f32_e32 v62, 0x3fb8aa3b, v62
	v_exp_f32_e32 v62, v62
	v_mul_f32_e32 v61, 0.5, v61
	v_add_f32_e32 v62, 1.0, v62
	v_rcp_f32_e32 v62, v62
	s_nop 0
	v_fma_f32 v62, v62, -2.0, 1.0
	v_add_f32_e32 v62, 1.0, v62
	v_mul_f32_e32 v61, v61, v62
	v_mul_f32_e32 v61, v70, v61
	v_cvt_pk_bf16_f32 v61, v61, s0
	global_store_short v[56:57], v61, off
	v_add_u32_e32 v56, 26, v60
	v_ashrrev_i32_e32 v57, 31, v56
	v_lshl_add_u64 v[56:57], s[34:35], 0, v[56:57]
	v_mad_u64_u32 v[62:63], s[0:1], v56, s52, v[4:5]
	v_mad_i32_i24 v63, v57, s52, v63
	v_lshl_add_u64 v[62:63], v[62:63], 0, v[2:3]
	v_mov_b32_e32 v59, v210
	v_lshlrev_b64 v[56:57], 11, v[56:57]
	v_lshl_add_u64 v[56:57], v[0:1], 0, v[56:57]
	s_nop 0
	v_lshlrev_b32_e32 v59, 16, v59
	v_mul_f32_e32 v61, 0x3d372713, v59
	v_mul_f32_e32 v61, v61, v59
	v_fma_f32 v61, v61, v59, v59
	v_mul_f32_e32 v61, 0x3f4c422a, v61
	v_add_f32_e32 v61, v61, v61
	v_mul_f32_e32 v61, 0x3fb8aa3b, v61
	v_exp_f32_e32 v61, v61
	v_mul_f32_e32 v59, 0.5, v59
	v_add_f32_e32 v61, 1.0, v61
	v_rcp_f32_e32 v61, v61
	s_nop 0
	v_fma_f32 v61, v61, -2.0, 1.0
	v_add_f32_e32 v61, 1.0, v61
	v_mul_f32_e32 v59, v59, v61
	v_mul_f32_e32 v58, v58, v59
	v_cvt_pk_bf16_f32 v58, v58, s0
	global_store_short v[56:57], v58, off
	v_add_u32_e32 v56, 27, v60
	v_ashrrev_i32_e32 v57, 31, v56
	v_fma_f32 v58, v30, v31, v6
	v_lshl_add_u64 v[30:31], s[34:35], 0, v[56:57]
	v_mad_u64_u32 v[56:57], s[0:1], v30, s52, v[4:5]
	v_mad_i32_i24 v57, v31, s52, v57
	v_lshl_add_u64 v[56:57], v[56:57], 0, v[2:3]
	v_mov_b32_e32 v56, v211
	v_lshlrev_b64 v[30:31], 11, v[30:31]
	v_lshl_add_u64 v[30:31], v[0:1], 0, v[30:31]
	s_nop 0
	v_lshlrev_b32_e32 v56, 16, v56
	v_mul_f32_e32 v57, 0x3d372713, v56
	v_mul_f32_e32 v57, v57, v56
	v_fma_f32 v57, v57, v56, v56
	v_mul_f32_e32 v57, 0x3f4c422a, v57
	v_add_f32_e32 v57, v57, v57
	v_mul_f32_e32 v57, 0x3fb8aa3b, v57
	v_exp_f32_e32 v57, v57
	v_mul_f32_e32 v56, 0.5, v56
	v_add_f32_e32 v57, 1.0, v57
	v_rcp_f32_e32 v57, v57
	s_nop 0
	v_fma_f32 v57, v57, -2.0, 1.0
	v_add_f32_e32 v57, 1.0, v57
	v_mul_f32_e32 v56, v56, v57
	v_mul_f32_e32 v56, v58, v56
	v_cvt_pk_bf16_f32 v56, v56, s0
	global_store_short v[30:31], v56, off
; DI u16 f2bf(float f) { return (u16)(pack2(f, 0.f) & 0xffffu); }
; DI float bf2f(u16 h) { return __uint_as_float(((uint32_t)h) << 16); }
; DI int launder(int v) { asm volatile("" : "+v"(v)); return v; }
; template <int M> DI float shxf(float v) { return __int_as_float(shxi<M>(__float_as_int(v))); }
; template <bool FINAL>
; DI void lru_item(int ws, PP p, char* shm, int item) {
;     ...
;         float P = 1.f, H = 0.f;
; #pragma unroll
;         for (int e = 0; e < 4; ++e) {
;           const int idx = 4 * q + e;
;           H = ar[mb][idx] * H + ai[mb][idx];
;           P *= ar[mb][idx];
;           ar[mb][idx] = P;
;           ai[mb][idx] = H;
;         }
;         const float Po = shxf<32>(P), Ho = shxf<32>(H);
;         const float A0 = hh ? Po : P, B0 = hh ? Ho : H, A1 = hh ? P : Po, B1 = hh ? H : Ho;
;         const float mid = B0 + A0 * carry;
;         const float cin = hh ? mid : carry;
;         carry = B1 + A1 * mid;
;         atot *= A0 * A1;
;         if (FINAL) {
;           const int tl0 = launder(hh * 4);
; #pragma unroll
;           for (int e = 0; e < 4; ++e) {
;             const int idx = 4 * q + e;
;             const int tok = mb * 32 + tl0 + e + 8 * q;
;             const float hv = ai[mb][idx] + ar[mb][idx] * cin;
;             const long trow = (long)b * SEQ + t0 + tok;
;             const float g = bf2f(u[trow * IN0 + 512 + chj]);
;             wt16(p->h + trow * DM + chj, f2bf(hv * gelu_tanh(g)));
;           }
	v_mul_f32_e32 v56, v48, v45
	v_fmac_f32_e32 v56, v50, v47
	v_mul_f32_e32 v50, v46, v48
	v_mul_f32_e32 v48, v51, v50
	v_cndmask_b32_e64 v31, v6, v7, s[10:11]
	v_mul_f32_e32 v47, v51, v56
	v_mul_f32_e32 v30, v54, v48
	v_fmac_f32_e32 v31, v29, v28
	v_fmac_f32_e32 v47, v53, v49
	v_mov_b32_e32 v7, v30
	v_mov_b32_e32 v28, v30
	v_mul_f32_e32 v6, v54, v47
	s_nop 0
	v_permlane32_swap_b32_e32 v7, v28
	v_fmac_f32_e32 v6, v55, v52
	v_xor_b32_e32 v7, v28, v7
	v_xor_b32_e32 v29, v7, v30
	v_mov_b32_e32 v7, v6
	v_mov_b32_e32 v28, v6
	s_nop 1
	v_permlane32_swap_b32_e32 v7, v28
	v_xor_b32_e32 v7, v28, v7
	v_xor_b32_e32 v7, v7, v6
	v_cndmask_b32_e64 v49, v29, v30, s[10:11]
	v_cndmask_b32_e64 v28, v7, v6, s[10:11]
	v_fmac_f32_e32 v28, v31, v49
	v_mov_b32_e32 v49, v86
	v_cndmask_b32_e64 v31, v28, v31, s[10:11]
	v_add_u32_e32 v52, 32, v49
	v_ashrrev_i32_e32 v53, 31, v52
	v_lshl_add_u64 v[52:53], s[34:35], 0, v[52:53]
	v_mad_u64_u32 v[54:55], s[0:1], v52, s52, v[4:5]
	v_mad_i32_i24 v55, v53, s52, v55
	v_lshl_add_u64 v[54:55], v[54:55], 0, v[2:3]
	v_fmac_f32_e32 v45, v46, v31
	v_mov_b32_e32 v46, v212
	v_lshlrev_b64 v[52:53], 11, v[52:53]
	v_lshl_add_u64 v[52:53], v[0:1], 0, v[52:53]
	v_fmac_f32_e32 v56, v50, v31
	v_fmac_f32_e32 v47, v48, v31
	v_cndmask_b32_e64 v29, v30, v29, s[10:11]
	s_nop 0
	v_lshlrev_b32_e32 v46, 16, v46
	v_mul_f32_e32 v51, 0x3d372713, v46
	v_mul_f32_e32 v51, v51, v46
	v_fma_f32 v51, v51, v46, v46
	v_mul_f32_e32 v51, 0x3f4c422a, v51
	v_add_f32_e32 v51, v51, v51
	v_mul_f32_e32 v51, 0x3fb8aa3b, v51
	v_exp_f32_e32 v51, v51
	v_mul_f32_e32 v46, 0.5, v46
	v_add_f32_e32 v51, 1.0, v51
	v_rcp_f32_e32 v51, v51
	s_nop 0
	v_fma_f32 v51, v51, -2.0, 1.0
	v_add_f32_e32 v51, 1.0, v51
	v_mul_f32_e32 v46, v46, v51
	v_mul_f32_e32 v45, v45, v46
	v_cvt_pk_bf16_f32 v45, v45, s0
	global_store_short v[52:53], v45, off
	v_add_u32_e32 v52, 33, v49
	v_ashrrev_i32_e32 v53, 31, v52
	v_lshl_add_u64 v[50:51], s[34:35], 0, v[52:53]
	v_mad_u64_u32 v[52:53], s[0:1], v50, s52, v[4:5]
	v_mad_i32_i24 v53, v51, s52, v53
	v_lshl_add_u64 v[52:53], v[52:53], 0, v[2:3]
	v_mov_b32_e32 v45, v213
	v_lshlrev_b64 v[50:51], 11, v[50:51]
	v_lshl_add_u64 v[50:51], v[0:1], 0, v[50:51]
	s_nop 0
	v_lshlrev_b32_e32 v45, 16, v45
	v_mul_f32_e32 v46, 0x3d372713, v45
	v_mul_f32_e32 v46, v46, v45
	v_fma_f32 v46, v46, v45, v45
	v_mul_f32_e32 v46, 0x3f4c422a, v46
	v_add_f32_e32 v46, v46, v46
	v_mul_f32_e32 v46, 0x3fb8aa3b, v46
	v_exp_f32_e32 v46, v46
	v_mul_f32_e32 v45, 0.5, v45
	v_add_f32_e32 v46, 1.0, v46
	v_rcp_f32_e32 v46, v46
	s_nop 0
	v_fma_f32 v46, v46, -2.0, 1.0
	v_add_f32_e32 v46, 1.0, v46
	v_mul_f32_e32 v45, v45, v46
	v_mul_f32_e32 v45, v56, v45
	v_cvt_pk_bf16_f32 v45, v45, s0
	global_store_short v[50:51], v45, off
	v_add_u32_e32 v50, 34, v49
	v_ashrrev_i32_e32 v51, 31, v50
	v_lshl_add_u64 v[50:51], s[34:35], 0, v[50:51]
	v_mad_u64_u32 v[52:53], s[0:1], v50, s52, v[4:5]
	v_mad_i32_i24 v53, v51, s52, v53
	v_lshl_add_u64 v[52:53], v[52:53], 0, v[2:3]
	v_mov_b32_e32 v45, v214
	v_lshlrev_b64 v[50:51], 11, v[50:51]
	v_lshl_add_u64 v[50:51], v[0:1], 0, v[50:51]
	s_nop 0
	v_lshlrev_b32_e32 v45, 16, v45
	v_mul_f32_e32 v46, 0x3d372713, v45
	v_mul_f32_e32 v46, v46, v45
	v_fma_f32 v46, v46, v45, v45
	v_mul_f32_e32 v46, 0x3f4c422a, v46
	v_add_f32_e32 v46, v46, v46
	v_mul_f32_e32 v46, 0x3fb8aa3b, v46
	v_exp_f32_e32 v46, v46
	v_mul_f32_e32 v45, 0.5, v45
	v_add_f32_e32 v46, 1.0, v46
	v_rcp_f32_e32 v46, v46
	s_nop 0
	v_fma_f32 v46, v46, -2.0, 1.0
	v_add_f32_e32 v46, 1.0, v46
	v_mul_f32_e32 v45, v45, v46
	v_mul_f32_e32 v45, v47, v45
	v_add_u32_e32 v46, 35, v49
	v_cvt_pk_bf16_f32 v45, v45, s0
	v_ashrrev_i32_e32 v47, 31, v46
	global_store_short v[50:51], v45, off
	v_fma_f32 v45, v30, v31, v6
	v_lshl_add_u64 v[30:31], s[34:35], 0, v[46:47]
	v_mad_u64_u32 v[46:47], s[0:1], v30, s52, v[4:5]
	v_mad_i32_i24 v47, v31, s52, v47
	v_lshl_add_u64 v[46:47], v[46:47], 0, v[2:3]
	v_mov_b32_e32 v46, v215
	v_lshlrev_b64 v[30:31], 11, v[30:31]
	v_lshl_add_u64 v[30:31], v[0:1], 0, v[30:31]
	s_nop 0
	v_lshlrev_b32_e32 v46, 16, v46
	v_mul_f32_e32 v47, 0x3d372713, v46
	v_mul_f32_e32 v47, v47, v46
	v_fma_f32 v47, v47, v46, v46
	v_mul_f32_e32 v47, 0x3f4c422a, v47
	v_add_f32_e32 v47, v47, v47
	v_mul_f32_e32 v47, 0x3fb8aa3b, v47
	v_exp_f32_e32 v47, v47
	v_mul_f32_e32 v46, 0.5, v46
	v_add_f32_e32 v47, 1.0, v47
	v_rcp_f32_e32 v47, v47
	s_nop 0
	v_fma_f32 v47, v47, -2.0, 1.0
	v_add_f32_e32 v47, 1.0, v47
	v_mul_f32_e32 v46, v46, v47
	v_mul_f32_e32 v45, v45, v46
	v_cvt_pk_bf16_f32 v45, v45, s0
	global_store_short v[30:31], v45, off
	v_mul_f32_e32 v45, v37, v34
	v_fmac_f32_e32 v45, v39, v36
	v_mul_f32_e32 v39, v35, v37
	v_mul_f32_e32 v37, v40, v39
	v_cndmask_b32_e64 v31, v6, v7, s[10:11]
	v_mul_f32_e32 v36, v40, v45
	v_mul_f32_e32 v30, v43, v37
	v_fmac_f32_e32 v31, v29, v28
	v_fmac_f32_e32 v36, v42, v38
	v_mov_b32_e32 v7, v30
	v_mov_b32_e32 v28, v30
	v_mul_f32_e32 v6, v43, v36
	s_nop 0
	v_permlane32_swap_b32_e32 v7, v28
	v_fmac_f32_e32 v6, v44, v41
	v_xor_b32_e32 v7, v28, v7
	v_xor_b32_e32 v29, v7, v30
	v_mov_b32_e32 v7, v6
	v_mov_b32_e32 v28, v6
	s_nop 1
	v_permlane32_swap_b32_e32 v7, v28
	v_xor_b32_e32 v7, v28, v7
	v_xor_b32_e32 v7, v7, v6
	v_cndmask_b32_e64 v38, v29, v30, s[10:11]
	v_cndmask_b32_e64 v28, v7, v6, s[10:11]
	v_fmac_f32_e32 v28, v31, v38
	v_mov_b32_e32 v38, v86
	v_cndmask_b32_e64 v31, v28, v31, s[10:11]
	v_add_u32_e32 v40, 40, v38
	v_ashrrev_i32_e32 v41, 31, v40
	v_lshl_add_u64 v[40:41], s[34:35], 0, v[40:41]
	v_mad_u64_u32 v[42:43], s[0:1], v40, s52, v[4:5]
	v_mad_i32_i24 v43, v41, s52, v43
	v_lshl_add_u64 v[42:43], v[42:43], 0, v[2:3]
	v_fmac_f32_e32 v34, v35, v31
	v_mov_b32_e32 v35, v216
	v_lshlrev_b64 v[40:41], 11, v[40:41]
; DI u16 f2bf(float f) { return (u16)(pack2(f, 0.f) & 0xffffu); }
; DI float bf2f(u16 h) { return __uint_as_float(((uint32_t)h) << 16); }
; DI int launder(int v) { asm volatile("" : "+v"(v)); return v; }
; template <int M> DI float shxf(float v) { return __int_as_float(shxi<M>(__float_as_int(v))); }
; template <bool FINAL>
; DI void lru_item(int ws, PP p, char* shm, int item) {
;     ...
;         float P = 1.f, H = 0.f;
; #pragma unroll
;         for (int e = 0; e < 4; ++e) {
;           const int idx = 4 * q + e;
;           H = ar[mb][idx] * H + ai[mb][idx];
;           P *= ar[mb][idx];
;           ar[mb][idx] = P;
;           ai[mb][idx] = H;
;         }
;         const float Po = shxf<32>(P), Ho = shxf<32>(H);
;         const float A0 = hh ? Po : P, B0 = hh ? Ho : H, A1 = hh ? P : Po, B1 = hh ? H : Ho;
;         const float mid = B0 + A0 * carry;
;         const float cin = hh ? mid : carry;
;         carry = B1 + A1 * mid;
;         atot *= A0 * A1;
;         if (FINAL) {
;           const int tl0 = launder(hh * 4);
; #pragma unroll
;           for (int e = 0; e < 4; ++e) {
;             const int idx = 4 * q + e;
;             const int tok = mb * 32 + tl0 + e + 8 * q;
;             const float hv = ai[mb][idx] + ar[mb][idx] * cin;
;             const long trow = (long)b * SEQ + t0 + tok;
;             const float g = bf2f(u[trow * IN0 + 512 + chj]);
;             wt16(p->h + trow * DM + chj, f2bf(hv * gelu_tanh(g)));
;           }
	v_lshl_add_u64 v[40:41], v[0:1], 0, v[40:41]
	v_fmac_f32_e32 v45, v39, v31
	v_fmac_f32_e32 v36, v37, v31
	v_cndmask_b32_e64 v29, v30, v29, s[10:11]
	s_nop 0
	v_lshlrev_b32_e32 v35, 16, v35
	v_mul_f32_e32 v42, 0x3d372713, v35
	v_mul_f32_e32 v42, v42, v35
	v_fma_f32 v42, v42, v35, v35
	v_mul_f32_e32 v42, 0x3f4c422a, v42
	v_add_f32_e32 v42, v42, v42
	v_mul_f32_e32 v42, 0x3fb8aa3b, v42
	v_exp_f32_e32 v42, v42
	v_mul_f32_e32 v35, 0.5, v35
	v_add_f32_e32 v42, 1.0, v42
	v_rcp_f32_e32 v42, v42
	s_nop 0
	v_fma_f32 v42, v42, -2.0, 1.0
	v_add_f32_e32 v42, 1.0, v42
	v_mul_f32_e32 v35, v35, v42
	v_mul_f32_e32 v34, v34, v35
	v_cvt_pk_bf16_f32 v34, v34, s0
	global_store_short v[40:41], v34, off
	v_add_u32_e32 v34, 41, v38
	v_ashrrev_i32_e32 v35, 31, v34
	v_lshl_add_u64 v[34:35], s[34:35], 0, v[34:35]
	v_mad_u64_u32 v[40:41], s[0:1], v34, s52, v[4:5]
	v_mad_i32_i24 v41, v35, s52, v41
	v_lshl_add_u64 v[40:41], v[40:41], 0, v[2:3]
	v_mov_b32_e32 v39, v217
	v_lshlrev_b64 v[34:35], 11, v[34:35]
	v_lshl_add_u64 v[34:35], v[0:1], 0, v[34:35]
	s_nop 0
	v_lshlrev_b32_e32 v39, 16, v39
	v_mul_f32_e32 v40, 0x3d372713, v39
	v_mul_f32_e32 v40, v40, v39
	v_fma_f32 v40, v40, v39, v39
	v_mul_f32_e32 v40, 0x3f4c422a, v40
	v_add_f32_e32 v40, v40, v40
	v_mul_f32_e32 v40, 0x3fb8aa3b, v40
	v_exp_f32_e32 v40, v40
	v_mul_f32_e32 v39, 0.5, v39
	v_add_f32_e32 v40, 1.0, v40
	v_rcp_f32_e32 v40, v40
	s_nop 0
	v_fma_f32 v40, v40, -2.0, 1.0
	v_add_f32_e32 v40, 1.0, v40
	v_mul_f32_e32 v39, v39, v40
	v_mul_f32_e32 v39, v45, v39
	v_cvt_pk_bf16_f32 v39, v39, s0
	global_store_short v[34:35], v39, off
	v_add_u32_e32 v34, 42, v38
	v_ashrrev_i32_e32 v35, 31, v34
	v_lshl_add_u64 v[34:35], s[34:35], 0, v[34:35]
	v_mad_u64_u32 v[40:41], s[0:1], v34, s52, v[4:5]
	v_mad_i32_i24 v41, v35, s52, v41
	v_lshl_add_u64 v[40:41], v[40:41], 0, v[2:3]
	v_mov_b32_e32 v37, v218
	v_lshlrev_b64 v[34:35], 11, v[34:35]
	v_lshl_add_u64 v[34:35], v[0:1], 0, v[34:35]
	s_nop 0
	v_lshlrev_b32_e32 v37, 16, v37
	v_mul_f32_e32 v39, 0x3d372713, v37
	v_mul_f32_e32 v39, v39, v37
	v_fma_f32 v39, v39, v37, v37
	v_mul_f32_e32 v39, 0x3f4c422a, v39
	v_add_f32_e32 v39, v39, v39
	v_mul_f32_e32 v39, 0x3fb8aa3b, v39
	v_exp_f32_e32 v39, v39
	v_mul_f32_e32 v37, 0.5, v37
	v_add_f32_e32 v39, 1.0, v39
	v_rcp_f32_e32 v39, v39
	s_nop 0
	v_fma_f32 v39, v39, -2.0, 1.0
	v_add_f32_e32 v39, 1.0, v39
	v_mul_f32_e32 v37, v37, v39
	v_mul_f32_e32 v36, v36, v37
	v_cvt_pk_bf16_f32 v36, v36, s0
	global_store_short v[34:35], v36, off
	v_add_u32_e32 v34, 43, v38
	v_ashrrev_i32_e32 v35, 31, v34
	v_fma_f32 v36, v30, v31, v6
	v_lshl_add_u64 v[30:31], s[34:35], 0, v[34:35]
	v_mad_u64_u32 v[34:35], s[0:1], v30, s52, v[4:5]
	v_mad_i32_i24 v35, v31, s52, v35
	v_lshl_add_u64 v[34:35], v[34:35], 0, v[2:3]
	v_mov_b32_e32 v34, v219
	v_lshlrev_b64 v[30:31], 11, v[30:31]
	v_lshl_add_u64 v[30:31], v[0:1], 0, v[30:31]
	s_nop 0
	v_lshlrev_b32_e32 v34, 16, v34
	v_mul_f32_e32 v35, 0x3d372713, v34
	v_mul_f32_e32 v35, v35, v34
	v_fma_f32 v35, v35, v34, v34
	v_mul_f32_e32 v35, 0x3f4c422a, v35
	v_add_f32_e32 v35, v35, v35
	v_mul_f32_e32 v35, 0x3fb8aa3b, v35
	v_exp_f32_e32 v35, v35
	v_mul_f32_e32 v34, 0.5, v34
	v_add_f32_e32 v35, 1.0, v35
	v_rcp_f32_e32 v35, v35
	s_nop 0
	v_fma_f32 v35, v35, -2.0, 1.0
	v_add_f32_e32 v35, 1.0, v35
	v_mul_f32_e32 v34, v34, v35
	v_mul_f32_e32 v34, v36, v34
	v_cvt_pk_bf16_f32 v34, v34, s0
	global_store_short v[30:31], v34, off
	v_cndmask_b32_e64 v31, v6, v7, s[10:11]
	v_fmac_f32_e32 v31, v29, v28
	v_mul_f32_e32 v29, v22, v19
	v_fmac_f32_e32 v29, v24, v21
	v_mul_f32_e32 v30, v20, v22
	v_mul_f32_e32 v28, v25, v29
	v_mul_f32_e32 v25, v25, v30
	v_fmac_f32_e32 v28, v32, v23
	v_mul_f32_e32 v23, v27, v25
	v_mov_b32_e32 v7, v23
	v_mov_b32_e32 v21, v23
	v_mul_f32_e32 v6, v27, v28
	s_nop 0
	v_permlane32_swap_b32_e32 v7, v21
	v_fmac_f32_e32 v6, v33, v26
	v_xor_b32_e32 v7, v21, v7
	v_xor_b32_e32 v22, v7, v23
	v_mov_b32_e32 v7, v6
	v_mov_b32_e32 v21, v6
	v_mov_b32_e32 v26, v86
	s_nop 0
	v_permlane32_swap_b32_e32 v7, v21
	v_xor_b32_e32 v7, v21, v7
	v_add_u32_e32 v32, 48, v26
	v_ashrrev_i32_e32 v33, 31, v32
	v_xor_b32_e32 v7, v7, v6
	v_lshl_add_u64 v[32:33], s[34:35], 0, v[32:33]
	v_cndmask_b32_e64 v24, v22, v23, s[10:11]
	v_cndmask_b32_e64 v21, v7, v6, s[10:11]
	v_mad_u64_u32 v[34:35], s[0:1], v32, s52, v[4:5]
	v_fmac_f32_e32 v21, v31, v24
	v_mad_i32_i24 v35, v33, s52, v35
	v_cndmask_b32_e64 v24, v21, v31, s[10:11]
	v_lshl_add_u64 v[34:35], v[34:35], 0, v[2:3]
	v_fmac_f32_e32 v19, v20, v24
	v_mov_b32_e32 v20, v220
	v_lshlrev_b64 v[32:33], 11, v[32:33]
	v_lshl_add_u64 v[32:33], v[0:1], 0, v[32:33]
	v_fmac_f32_e32 v29, v30, v24
	v_fmac_f32_e32 v28, v25, v24
	v_cndmask_b32_e64 v22, v23, v22, s[10:11]
	s_nop 0
	v_lshlrev_b32_e32 v20, 16, v20
	v_mul_f32_e32 v27, 0x3d372713, v20
	v_mul_f32_e32 v27, v27, v20
	v_fma_f32 v27, v27, v20, v20
	v_mul_f32_e32 v27, 0x3f4c422a, v27
	v_add_f32_e32 v27, v27, v27
	v_mul_f32_e32 v27, 0x3fb8aa3b, v27
	v_exp_f32_e32 v27, v27
	v_mul_f32_e32 v20, 0.5, v20
	v_add_f32_e32 v27, 1.0, v27
	v_rcp_f32_e32 v27, v27
	s_nop 0
	v_fma_f32 v27, v27, -2.0, 1.0
	v_add_f32_e32 v27, 1.0, v27
	v_mul_f32_e32 v20, v20, v27
	v_mul_f32_e32 v19, v19, v20
	v_cvt_pk_bf16_f32 v19, v19, s0
	global_store_short v[32:33], v19, off
	v_add_u32_e32 v32, 49, v26
	v_ashrrev_i32_e32 v33, 31, v32
	v_lshl_add_u64 v[30:31], s[34:35], 0, v[32:33]
	v_mad_u64_u32 v[32:33], s[0:1], v30, s52, v[4:5]
	v_mad_i32_i24 v33, v31, s52, v33
	v_lshl_add_u64 v[32:33], v[32:33], 0, v[2:3]
	v_mov_b32_e32 v19, v221
	v_lshlrev_b64 v[30:31], 11, v[30:31]
	v_lshl_add_u64 v[30:31], v[0:1], 0, v[30:31]
	s_nop 0
	v_lshlrev_b32_e32 v19, 16, v19
	v_mul_f32_e32 v20, 0x3d372713, v19
; DI u16 f2bf(float f) { return (u16)(pack2(f, 0.f) & 0xffffu); }
; DI float bf2f(u16 h) { return __uint_as_float(((uint32_t)h) << 16); }
; DI int launder(int v) { asm volatile("" : "+v"(v)); return v; }
; template <int M> DI float shxf(float v) { return __int_as_float(shxi<M>(__float_as_int(v))); }
; template <bool FINAL>
; DI void lru_item(int ws, PP p, char* shm, int item) {
;     ...
;         float P = 1.f, H = 0.f;
; #pragma unroll
;         for (int e = 0; e < 4; ++e) {
;           const int idx = 4 * q + e;
;           H = ar[mb][idx] * H + ai[mb][idx];
;           P *= ar[mb][idx];
;           ar[mb][idx] = P;
;           ai[mb][idx] = H;
;         }
;         const float Po = shxf<32>(P), Ho = shxf<32>(H);
;         const float A0 = hh ? Po : P, B0 = hh ? Ho : H, A1 = hh ? P : Po, B1 = hh ? H : Ho;
;         const float mid = B0 + A0 * carry;
;         const float cin = hh ? mid : carry;
;         carry = B1 + A1 * mid;
;         atot *= A0 * A1;
;         if (FINAL) {
;           const int tl0 = launder(hh * 4);
; #pragma unroll
;           for (int e = 0; e < 4; ++e) {
;             const int idx = 4 * q + e;
;             const int tok = mb * 32 + tl0 + e + 8 * q;
;             const float hv = ai[mb][idx] + ar[mb][idx] * cin;
;             const long trow = (long)b * SEQ + t0 + tok;
;             const float g = bf2f(u[trow * IN0 + 512 + chj]);
;             wt16(p->h + trow * DM + chj, f2bf(hv * gelu_tanh(g)));
;           }
;         }
;       }
;     if (!FINAL && hh == 0) {
;       float2 ab = {atot, carry};
;       wt64(p->lrusum + (((long)b * 128 + c) * 512 + chj) * 2, __builtin_bit_cast(u32x2, ab));
	v_mul_f32_e32 v20, v20, v19
	v_fma_f32 v20, v20, v19, v19
	v_mul_f32_e32 v20, 0x3f4c422a, v20
	v_add_f32_e32 v20, v20, v20
	v_mul_f32_e32 v20, 0x3fb8aa3b, v20
	v_exp_f32_e32 v20, v20
	v_mul_f32_e32 v19, 0.5, v19
	v_add_f32_e32 v20, 1.0, v20
	v_rcp_f32_e32 v20, v20
	s_nop 0
	v_fma_f32 v20, v20, -2.0, 1.0
	v_add_f32_e32 v20, 1.0, v20
	v_mul_f32_e32 v19, v19, v20
	v_mul_f32_e32 v19, v29, v19
	v_cvt_pk_bf16_f32 v19, v19, s0
	global_store_short v[30:31], v19, off
	v_add_u32_e32 v30, 50, v26
	v_ashrrev_i32_e32 v31, 31, v30
	v_lshl_add_u64 v[30:31], s[34:35], 0, v[30:31]
	v_mad_u64_u32 v[32:33], s[0:1], v30, s52, v[4:5]
	v_mad_i32_i24 v33, v31, s52, v33
	v_lshl_add_u64 v[32:33], v[32:33], 0, v[2:3]
	v_mov_b32_e32 v19, v222
	v_lshlrev_b64 v[30:31], 11, v[30:31]
	v_add_u32_e32 v26, 51, v26
	v_lshl_add_u64 v[30:31], v[0:1], 0, v[30:31]
	v_ashrrev_i32_e32 v27, 31, v26
	s_nop 0
	v_lshlrev_b32_e32 v19, 16, v19
	v_mul_f32_e32 v20, 0x3d372713, v19
	v_mul_f32_e32 v20, v20, v19
	v_fma_f32 v20, v20, v19, v19
	v_mul_f32_e32 v20, 0x3f4c422a, v20
	v_add_f32_e32 v20, v20, v20
	v_mul_f32_e32 v20, 0x3fb8aa3b, v20
	v_exp_f32_e32 v20, v20
	v_mul_f32_e32 v19, 0.5, v19
	v_add_f32_e32 v20, 1.0, v20
	v_rcp_f32_e32 v20, v20
	s_nop 0
	v_fma_f32 v20, v20, -2.0, 1.0
	v_add_f32_e32 v20, 1.0, v20
	v_mul_f32_e32 v19, v19, v20
	v_mul_f32_e32 v19, v28, v19
	v_cvt_pk_bf16_f32 v19, v19, s0
	global_store_short v[30:31], v19, off
	v_fma_f32 v19, v23, v24, v6
	v_lshl_add_u64 v[24:25], s[34:35], 0, v[26:27]
	v_mad_u64_u32 v[26:27], s[0:1], v24, s52, v[4:5]
	v_mad_i32_i24 v27, v25, s52, v27
	v_lshl_add_u64 v[26:27], v[26:27], 0, v[2:3]
	v_mov_b32_e32 v20, v223
	v_lshlrev_b64 v[24:25], 11, v[24:25]
	v_lshl_add_u64 v[24:25], v[0:1], 0, v[24:25]
	s_nop 0
	v_lshlrev_b32_e32 v20, 16, v20
	v_mul_f32_e32 v23, 0x3d372713, v20
	v_mul_f32_e32 v23, v23, v20
	v_fma_f32 v23, v23, v20, v20
	v_mul_f32_e32 v23, 0x3f4c422a, v23
	v_add_f32_e32 v23, v23, v23
	v_mul_f32_e32 v23, 0x3fb8aa3b, v23
	v_exp_f32_e32 v23, v23
	v_mul_f32_e32 v20, 0.5, v20
	v_add_f32_e32 v23, 1.0, v23
	v_rcp_f32_e32 v23, v23
	s_nop 0
	v_fma_f32 v23, v23, -2.0, 1.0
	v_add_f32_e32 v23, 1.0, v23
	v_mul_f32_e32 v20, v20, v23
	v_mul_f32_e32 v19, v19, v20
	v_cvt_pk_bf16_f32 v19, v19, s0
	global_store_short v[24:25], v19, off
	v_mul_f32_e32 v19, v11, v8
	v_fmac_f32_e32 v19, v13, v10
	v_mul_f32_e32 v20, v9, v11
	v_mul_f32_e32 v11, v14, v19
	v_fmac_f32_e32 v11, v17, v12
	v_mul_f32_e32 v12, v14, v20
	v_cndmask_b32_e64 v23, v6, v7, s[10:11]
	v_mul_f32_e32 v7, v15, v12
	v_mul_f32_e32 v6, v15, v11
	v_mov_b32_e32 v10, v7
	v_mov_b32_e32 v13, v7
	v_fmac_f32_e32 v6, v18, v16
	s_nop 0
	v_permlane32_swap_b32_e32 v10, v13
	v_xor_b32_e32 v10, v13, v10
	v_mov_b32_e32 v13, v6
	v_mov_b32_e32 v14, v6
	s_nop 1
	v_permlane32_swap_b32_e32 v13, v14
	v_xor_b32_e32 v10, v10, v7
	v_xor_b32_e32 v13, v14, v13
	v_fmac_f32_e32 v23, v22, v21
	v_xor_b32_e32 v13, v13, v6
	v_cndmask_b32_e64 v10, v10, v7, s[10:11]
	v_fmac_f32_e32 v13, v23, v10
	v_cndmask_b32_e64 v10, v13, v23, s[10:11]
	v_mov_b32_e32 v13, v86
	v_fmac_f32_e32 v8, v9, v10
	v_add_u32_e32 v14, 56, v13
	v_ashrrev_i32_e32 v15, 31, v14
	v_lshl_add_u64 v[14:15], s[34:35], 0, v[14:15]
	v_mad_u64_u32 v[16:17], s[0:1], v14, s52, v[4:5]
	v_mad_i32_i24 v17, v15, s52, v17
	v_lshl_add_u64 v[16:17], v[16:17], 0, v[2:3]
	v_mov_b32_e32 v9, v224
	v_lshlrev_b64 v[14:15], 11, v[14:15]
	v_lshl_add_u64 v[14:15], v[0:1], 0, v[14:15]
	v_fmac_f32_e32 v19, v20, v10
	v_fmac_f32_e32 v11, v12, v10
	v_fmac_f32_e32 v6, v7, v10
	s_nop 0
	v_lshlrev_b32_e32 v9, 16, v9
	v_mul_f32_e32 v16, 0x3d372713, v9
	v_mul_f32_e32 v16, v16, v9
	v_fma_f32 v16, v16, v9, v9
	v_mul_f32_e32 v16, 0x3f4c422a, v16
	v_add_f32_e32 v16, v16, v16
	v_mul_f32_e32 v16, 0x3fb8aa3b, v16
	v_exp_f32_e32 v16, v16
	v_mul_f32_e32 v9, 0.5, v9
	v_add_f32_e32 v16, 1.0, v16
	v_rcp_f32_e32 v16, v16
	s_nop 0
	v_fma_f32 v16, v16, -2.0, 1.0
	v_add_f32_e32 v16, 1.0, v16
	v_mul_f32_e32 v9, v9, v16
	v_mul_f32_e32 v8, v8, v9
	v_cvt_pk_bf16_f32 v8, v8, s0
	global_store_short v[14:15], v8, off
	v_add_u32_e32 v8, 57, v13
	v_ashrrev_i32_e32 v9, 31, v8
	v_lshl_add_u64 v[8:9], s[34:35], 0, v[8:9]
	v_mad_u64_u32 v[14:15], s[0:1], v8, s52, v[4:5]
	v_mad_i32_i24 v15, v9, s52, v15
	v_lshl_add_u64 v[14:15], v[14:15], 0, v[2:3]
	v_mov_b32_e32 v14, v225
	v_lshlrev_b64 v[8:9], 11, v[8:9]
	v_lshl_add_u64 v[8:9], v[0:1], 0, v[8:9]
	s_nop 0
	v_lshlrev_b32_e32 v14, 16, v14
	v_mul_f32_e32 v15, 0x3d372713, v14
	v_mul_f32_e32 v15, v15, v14
	v_fma_f32 v15, v15, v14, v14
	v_mul_f32_e32 v15, 0x3f4c422a, v15
	v_add_f32_e32 v15, v15, v15
	v_mul_f32_e32 v15, 0x3fb8aa3b, v15
	v_exp_f32_e32 v15, v15
	v_mul_f32_e32 v14, 0.5, v14
	v_add_f32_e32 v15, 1.0, v15
	v_rcp_f32_e32 v15, v15
	s_nop 0
	v_fma_f32 v15, v15, -2.0, 1.0
	v_add_f32_e32 v15, 1.0, v15
	v_mul_f32_e32 v14, v14, v15
	v_mul_f32_e32 v14, v19, v14
	v_cvt_pk_bf16_f32 v14, v14, s0
	global_store_short v[8:9], v14, off
	v_add_u32_e32 v8, 58, v13
	v_ashrrev_i32_e32 v9, 31, v8
	v_lshl_add_u64 v[8:9], s[34:35], 0, v[8:9]
	v_mad_u64_u32 v[14:15], s[0:1], v8, s52, v[4:5]
	v_mad_i32_i24 v15, v9, s52, v15
	v_lshl_add_u64 v[14:15], v[14:15], 0, v[2:3]
	v_mov_b32_e32 v12, v226
	v_lshlrev_b64 v[8:9], 11, v[8:9]
	v_lshl_add_u64 v[8:9], v[0:1], 0, v[8:9]
	s_nop 0
	v_lshlrev_b32_e32 v12, 16, v12
	v_mul_f32_e32 v14, 0x3d372713, v12
	v_mul_f32_e32 v14, v14, v12
	v_fma_f32 v14, v14, v12, v12
	v_mul_f32_e32 v14, 0x3f4c422a, v14
	v_add_f32_e32 v14, v14, v14
	v_mul_f32_e32 v14, 0x3fb8aa3b, v14
	v_exp_f32_e32 v14, v14
	v_mul_f32_e32 v12, 0.5, v12
	v_add_f32_e32 v14, 1.0, v14
	v_rcp_f32_e32 v14, v14
	s_nop 0
	v_fma_f32 v14, v14, -2.0, 1.0
	v_add_f32_e32 v14, 1.0, v14
	v_mul_f32_e32 v12, v12, v14
	v_mul_f32_e32 v11, v11, v12
	v_cvt_pk_bf16_f32 v11, v11, s0
	global_store_short v[8:9], v11, off
	v_add_u32_e32 v8, 59, v13
	v_ashrrev_i32_e32 v9, 31, v8
	v_lshl_add_u64 v[8:9], s[34:35], 0, v[8:9]
	v_mad_u64_u32 v[4:5], s[0:1], v8, s52, v[4:5]
	v_mad_i32_i24 v5, v9, s52, v5
	v_lshl_add_u64 v[2:3], v[4:5], 0, v[2:3]
	v_mov_b32_e32 v2, v227
	s_nop 0
	v_lshlrev_b32_e32 v4, 16, v2
	v_lshlrev_b64 v[2:3], 11, v[8:9]
	v_lshl_add_u64 v[0:1], v[0:1], 0, v[2:3]
	v_mul_f32_e32 v2, 0x3d372713, v4
	v_mul_f32_e32 v2, v2, v4
	v_fma_f32 v2, v2, v4, v4
	v_mul_f32_e32 v2, 0x3f4c422a, v2
	v_add_f32_e32 v2, v2, v2
	v_mul_f32_e32 v2, 0x3fb8aa3b, v2
	v_exp_f32_e32 v2, v2
	v_mul_f32_e32 v3, 0.5, v4
	v_add_f32_e32 v2, 1.0, v2
	v_rcp_f32_e32 v2, v2
	s_nop 0
	v_fma_f32 v2, v2, -2.0, 1.0
	v_add_f32_e32 v2, 1.0, v2
	v_mul_f32_e32 v2, v3, v2
	v_mul_f32_e32 v2, v6, v2
	v_cvt_pk_bf16_f32 v2, v2, s0
	global_store_short v[0:1], v2, off
	s_cbranch_vccnz .LBB0_683

; template <bool FINAL>
; DI void lru_item(int ws, PP p, char* shm, int item) {
;     ...
;     if (FINAL) {
;       const float* sm = p->lrusum + ((long)b * 128 * 512 + chj) * 2;
; #pragma unroll 8
;       for (int cp = 0; cp < c; ++cp) {
;         float2 ab = *(const float2*)(sm + (long)cp * 1024);
;         carry = ab.y + ab.x * carry;
;       }
.LBB0_678:
	s_movk_i32 s1, 0xd000
	v_add_co_u32_e32 v104, vcc, 0xffff9000, v76
	s_nop 1
	v_addc_co_u32_e32 v105, vcc, -1, v77, vcc
	global_load_dwordx2 v[230:231], v[104:105], off offset:-4
	v_add_co_u32_e32 v104, vcc, 0xffffa000, v76
	s_nop 1
	v_addc_co_u32_e32 v105, vcc, -1, v77, vcc
	global_load_dwordx2 v[232:233], v[104:105], off offset:-4
	v_add_co_u32_e32 v104, vcc, 0xffffb000, v76
	s_nop 1
	v_addc_co_u32_e32 v105, vcc, -1, v77, vcc
	global_load_dwordx2 v[234:235], v[104:105], off offset:-4
	v_add_co_u32_e32 v104, vcc, 0xffffc000, v76
	s_nop 1
	v_addc_co_u32_e32 v105, vcc, -1, v77, vcc
	global_load_dwordx2 v[236:237], v[104:105], off offset:-4
	v_add_co_u32_e32 v104, vcc, s1, v76
	s_nop 1
	v_addc_co_u32_e32 v105, vcc, -1, v77, vcc
	global_load_dwordx2 v[238:239], v[104:105], off offset:-4
	v_add_co_u32_e32 v104, vcc, 0xffffe000, v76
	s_nop 1
	v_addc_co_u32_e32 v105, vcc, -1, v77, vcc
	global_load_dwordx2 v[240:241], v[104:105], off offset:-4
	v_add_co_u32_e32 v104, vcc, 0xfffff000, v76
	s_nop 1
	v_addc_co_u32_e32 v105, vcc, -1, v77, vcc
	global_load_dwordx2 v[242:243], v[104:105], off offset:-4
	global_load_dwordx2 v[244:245], v[76:77], off offset:-4
	v_lshl_add_u64 v[76:77], v[76:77], 0, s[26:27]
	s_add_i32 s0, s0, 8
	s_waitcnt vmcnt(7)
	v_fmac_f32_e32 v231, v73, v230
	s_waitcnt vmcnt(6)
	v_fmac_f32_e32 v233, v231, v232
	s_waitcnt vmcnt(5)
	v_fmac_f32_e32 v235, v233, v234
	s_waitcnt vmcnt(4)
	v_fmac_f32_e32 v237, v235, v236
	s_waitcnt vmcnt(3)
	v_fmac_f32_e32 v239, v237, v238
	s_waitcnt vmcnt(2)
	v_fmac_f32_e32 v241, v239, v240
	s_waitcnt vmcnt(1)
	v_fmac_f32_e32 v243, v241, v242
	s_waitcnt vmcnt(0)
	v_fmac_f32_e32 v245, v243, v244
	v_mov_b32_e32 v73, v245
	s_cmp_eq_u32 s90, s0
	s_cbranch_scc0 .LBB0_678
	s_mov_b32 s22, s90
	s_andn2_b64 vcc, exec, s[42:43]
	s_cbranch_vccz .LBB0_681
	s_branch .LBB0_674

; __global__ void __launch_bounds__(NTHR) fwd_kernel(Params pk) {
;   __shared__ __attribute__((aligned(1024))) char shm[151552];
	.amdhsa_kernel _Z10fwd_kernel6Params
		.amdhsa_group_segment_fixed_size 151552
		.amdhsa_private_segment_fixed_size 0
		.amdhsa_kernarg_size 1928
		.amdhsa_user_sgpr_count 2
		.amdhsa_user_sgpr_dispatch_ptr 0
		.amdhsa_user_sgpr_queue_ptr 0
		.amdhsa_user_sgpr_kernarg_segment_ptr 1
		.amdhsa_user_sgpr_dispatch_id 0
		.amdhsa_user_sgpr_kernarg_preload_length 0
		.amdhsa_user_sgpr_kernarg_preload_offset 0
		.amdhsa_user_sgpr_private_segment_size 0
		.amdhsa_uses_dynamic_stack 0
		.amdhsa_enable_private_segment 0
		.amdhsa_system_sgpr_workgroup_id_x 1
		.amdhsa_system_sgpr_workgroup_id_y 0
		.amdhsa_system_sgpr_workgroup_id_z 0
		.amdhsa_system_sgpr_workgroup_info 0
		.amdhsa_system_vgpr_workitem_id 2
		.amdhsa_next_free_vgpr 256
		.amdhsa_next_free_sgpr 102
		.amdhsa_accum_offset 256
		.amdhsa_reserve_vcc 1
		.amdhsa_float_round_mode_32 0
		.amdhsa_float_round_mode_16_64 0
		.amdhsa_float_denorm_mode_32 3
		.amdhsa_float_denorm_mode_16_64 3
		.amdhsa_dx10_clamp 1
		.amdhsa_ieee_mode 1
		.amdhsa_fp16_overflow 0
		.amdhsa_tg_split 0
		.amdhsa_exception_fp_ieee_invalid_op 0
		.amdhsa_exception_fp_denorm_src 0
		.amdhsa_exception_fp_ieee_div_zero 0
		.amdhsa_exception_fp_ieee_overflow 0
		.amdhsa_exception_fp_ieee_underflow 0
		.amdhsa_exception_fp_ieee_inexact 0
		.amdhsa_exception_int_div_zero 0
	.end_amdhsa_kernel

; __global__ void __launch_bounds__(NTHR) fwd_kernel(Params pk) {
;   __shared__ __attribute__((aligned(1024))) char shm[151552];
amdhsa.kernels:
  - .agpr_count:     0
    .args:
      - .offset:         0
        .size:           1672
        .value_kind:     by_value
      - .offset:         1672
        .size:           4
        .value_kind:     hidden_block_count_x
      - .offset:         1676
        .size:           4
        .value_kind:     hidden_block_count_y
      - .offset:         1680
        .size:           4
        .value_kind:     hidden_block_count_z
      - .offset:         1684
        .size:           2
        .value_kind:     hidden_group_size_x
      - .offset:         1686
        .size:           2
        .value_kind:     hidden_group_size_y
      - .offset:         1688
        .size:           2
        .value_kind:     hidden_group_size_z
      - .offset:         1690
        .size:           2
        .value_kind:     hidden_remainder_x
      - .offset:         1692
        .size:           2
        .value_kind:     hidden_remainder_y
      - .offset:         1694
        .size:           2
        .value_kind:     hidden_remainder_z
      - .offset:         1712
        .size:           8
        .value_kind:     hidden_global_offset_x
      - .offset:         1720
        .size:           8
        .value_kind:     hidden_global_offset_y
      - .offset:         1728
        .size:           8
        .value_kind:     hidden_global_offset_z
      - .offset:         1736
        .size:           2
        .value_kind:     hidden_grid_dims
      - .offset:         1760
        .size:           8
        .value_kind:     hidden_multigrid_sync_arg
    .group_segment_fixed_size: 151552
    .kernarg_segment_align: 8
    .kernarg_segment_size: 1928
    .language:       OpenCL C
    .language_version:
      - 2
      - 0
    .max_flat_workgroup_size: 512
    .name:           _Z10fwd_kernel6Params
    .private_segment_fixed_size: 0
    .sgpr_count:     108
    .sgpr_spill_count: 23
    .symbol:         _Z10fwd_kernel6Params.kd
    .uniform_work_group_size: 1
    .uses_dynamic_stack: false
    .vgpr_count:     256
    .vgpr_spill_count: 0
    .wavefront_size: 64
